# v11 plus P3 state-unit K/V loads hoisted above the decay math and P5 prefix-state slices requested up front
# baseline (speedup 1.0000x reference)
.LBB0_275:
	global_load_dword v2, v67, s[16:17]
	global_load_dword v3, v67, s[16:17] offset:16
	s_or_b32 s5, s5, s36
	s_sub_i32 s72, s5, 64
	s_lshl_b32 s5, s5, 8
	s_lshl_b32 s22, s72, 6
	s_and_b32 s5, s5, 0x700
	s_and_b32 s22, s22, 0x7ffff800
	s_or_b32 s22, s22, s5
	s_add_i32 s5, s22, 0x1000
	v_add_u32_e32 v228, s5, v1
	v_mad_i64_i32 v[220:221], s[30:31], v228, s27, v[68:69]
	v_add_u32_e32 v229, s5, v90
	v_mad_i64_i32 v[222:223], s[30:31], v229, s27, v[68:69]
	v_add_u32_e32 v230, s5, v91
	v_mad_i64_i32 v[224:225], s[30:31], v230, s27, v[68:69]
	v_add_u32_e32 v231, s5, v92
	v_mad_i64_i32 v[226:227], s[30:31], v231, s27, v[68:69]
	global_load_dwordx4 v[184:187], v[220:221], off offset:1024
	global_load_dwordx4 v[188:191], v[220:221], off offset:2048
	global_load_dwordx4 v[192:195], v[222:223], off offset:1024
	global_load_dwordx4 v[196:199], v[222:223], off offset:2048
	global_load_dwordx4 v[200:203], v[224:225], off offset:1024
	global_load_dwordx4 v[204:207], v[224:225], off offset:2048
	global_load_dwordx4 v[208:211], v[226:227], off offset:1024
	global_load_dwordx4 v[216:219], v[226:227], off offset:2048
	v_readfirstlane_b32 s4, v130
	s_cmpk_lt_u32 s4, 0x100
	s_waitcnt vmcnt(9)
	v_mul_f32_e32 v4, 0xbfb8aa3b, v2
	s_waitcnt vmcnt(8)
	v_mul_f32_e32 v5, 0xbfb8aa3b, v3
	v_fma_f32 v6, v2, s0, -v4
	v_rndne_f32_e32 v7, v4
	v_fma_f32 v8, v3, s0, -v5
	v_rndne_f32_e32 v9, v5
	v_fmac_f32_e32 v6, 0xb2a5705f, v2
	v_sub_f32_e32 v4, v4, v7
	v_fmac_f32_e32 v8, 0xb2a5705f, v3
	v_sub_f32_e32 v5, v5, v9
	v_add_f32_e32 v4, v4, v6
	v_cvt_i32_f32_e32 v7, v7
	v_add_f32_e32 v5, v5, v8
	v_exp_f32_e32 v4, v4
	v_cvt_i32_f32_e32 v9, v9
	v_exp_f32_e32 v5, v5
	v_cmp_nlt_f32_e32 vcc, s1, v2
	v_ldexp_f32 v4, v4, v7
	v_ldexp_f32 v5, v5, v9
	v_cndmask_b32_e32 v4, 0, v4, vcc
	v_cmp_nlt_f32_e32 vcc, s1, v3
	s_nop 1
	v_cndmask_b32_e32 v5, 0, v5, vcc
	v_cmp_ngt_f32_e32 vcc, s10, v2
	s_nop 1
	v_cndmask_b32_e32 v18, v121, v4, vcc
	v_cmp_ngt_f32_e32 vcc, s10, v3
	v_add_f32_e32 v6, 1.0, v18
	v_frexp_mant_f32_e32 v8, v6
	v_cndmask_b32_e32 v28, v121, v5, vcc
	v_add_f32_e32 v19, 1.0, v28
	v_cvt_f64_f32_e32 v[2:3], v6
	v_add_f32_e32 v9, -1.0, v19
	v_frexp_exp_i32_f64_e32 v2, v[2:3]
	v_cmp_gt_f32_e32 vcc, s24, v8
	v_add_f32_e32 v7, -1.0, v6
	v_cvt_f64_f32_e32 v[4:5], v19
	v_sub_f32_e32 v3, v9, v19
	v_subbrev_co_u32_e32 v2, vcc, 0, v2, vcc
	v_sub_f32_e32 v10, v7, v6
	v_sub_f32_e32 v9, v28, v9
	v_frexp_exp_i32_f64_e32 v21, v[4:5]
	v_add_f32_e32 v3, 1.0, v3
	v_sub_u32_e32 v5, 0, v2
	v_sub_f32_e32 v7, v18, v7
	v_add_f32_e32 v4, 1.0, v10
	v_add_f32_e32 v22, v9, v3
	v_ldexp_f32 v3, v6, v5
	v_add_f32_e32 v4, v7, v4
	v_add_f32_e32 v6, -1.0, v3
	v_add_f32_e32 v7, 1.0, v3
	v_ldexp_f32 v4, v4, v5
	v_add_f32_e32 v5, 1.0, v6
	v_add_f32_e32 v8, -1.0, v7
	v_sub_f32_e32 v5, v3, v5
	v_sub_f32_e32 v3, v3, v8
	v_add_f32_e32 v3, v4, v3
	v_add_f32_e32 v10, v7, v3
	v_rcp_f32_e32 v11, v10
	v_add_f32_e32 v8, v4, v5
	v_add_f32_e32 v5, v6, v8
	v_sub_f32_e32 v6, v6, v5
	v_mul_f32_e32 v13, v5, v11
	v_sub_f32_e32 v4, v7, v10
	v_add_f32_e32 v12, v8, v6
	v_mul_f32_e32 v6, v10, v13
	v_add_f32_e32 v3, v3, v4
	v_fma_f32 v8, v13, v10, -v6
	v_fmac_f32_e32 v8, v13, v3
	v_add_f32_e32 v4, v6, v8
	v_sub_f32_e32 v7, v5, v4
	v_mov_b32_e32 v9, v4
	v_pk_add_f32 v[4:5], v[4:5], v[6:7] neg_lo:[0,1] neg_hi:[0,1]
	v_cvt_f32_i32_e32 v2, v2
	v_pk_add_f32 v[4:5], v[4:5], v[8:9] neg_lo:[0,1] neg_hi:[0,1]
	v_cmp_neq_f32_e32 vcc, s11, v18
	v_add_f32_e32 v5, v12, v5
	v_add_f32_e32 v4, v4, v5
	v_add_f32_e32 v5, v7, v4
	v_mul_f32_e32 v9, v11, v5
	v_mul_f32_e32 v6, v10, v9
	v_sub_f32_e32 v7, v7, v5
	v_add_f32_e32 v14, v13, v9
	v_fma_f32 v8, v9, v10, -v6
	v_add_f32_e32 v12, v4, v7
	v_sub_f32_e32 v4, v14, v13
	v_fmac_f32_e32 v8, v9, v3
	v_sub_f32_e32 v3, v9, v4
	v_add_f32_e32 v4, v6, v8
	v_sub_f32_e32 v7, v5, v4
	v_mov_b32_e32 v9, v4
	v_pk_add_f32 v[4:5], v[4:5], v[6:7] neg_lo:[0,1] neg_hi:[0,1]
	v_frexp_mant_f32_e32 v20, v19
	v_pk_add_f32 v[4:5], v[4:5], v[8:9] neg_lo:[0,1] neg_hi:[0,1]
	s_nop 0
	v_add_f32_e32 v5, v12, v5
	v_add_f32_e32 v4, v4, v5
	v_add_f32_e32 v4, v7, v4
	v_mul_f32_e32 v4, v11, v4
	v_add_f32_e32 v3, v3, v4
	v_add_f32_e32 v4, v14, v3
	v_mul_f32_e32 v6, v4, v4
	v_sub_f32_e32 v7, v4, v14
	v_fmamk_f32 v8, v6, 0x3e9b6dac, v120
	v_sub_f32_e32 v7, v3, v7
	v_mul_f32_e32 v3, v4, v6
	v_fmaak_f32 v87, v6, v8, 0x3f2aaada
	v_ldexp_f32 v9, v7, 1
	v_pk_mul_f32 v[6:7], v[2:3], v[86:87]
	v_ldexp_f32 v5, v4, 1
	v_fma_f32 v4, v2, s25, -v6
	v_fmac_f32_e32 v4, 0xb102e308, v2
	v_pk_add_f32 v[2:3], v[6:7], v[4:5]
	v_mov_b32_e32 v8, v6
	v_sub_f32_e32 v12, v3, v5
	v_pk_add_f32 v[10:11], v[2:3], v[6:7] neg_lo:[0,1] neg_hi:[0,1]
	v_sub_f32_e32 v7, v7, v12
	v_add_f32_e32 v9, v9, v7
	v_pk_add_f32 v[14:15], v[2:3], v[8:9]
	v_mov_b32_e32 v5, v2
	v_mov_b32_e32 v11, v15
	v_pk_add_f32 v[16:17], v[4:5], v[10:11] neg_lo:[0,1] neg_hi:[0,1]
	v_pk_add_f32 v[4:5], v[4:5], v[10:11]
	v_mov_b32_e32 v6, v3
	v_mov_b32_e32 v13, v2
	v_pk_add_f32 v[2:3], v[4:5], v[2:3] op_sel:[1,0] op_sel_hi:[0,1] neg_lo:[0,1] neg_hi:[0,1]
	v_mov_b32_e32 v12, v9
	v_mov_b32_e32 v8, v15
	v_mov_b32_e32 v9, v5
	v_mov_b32_e32 v7, v2
	v_pk_add_f32 v[10:11], v[14:15], v[2:3] op_sel_hi:[1,0] neg_lo:[0,1] neg_hi:[0,1]
	v_pk_add_f32 v[2:3], v[8:9], v[6:7] neg_lo:[0,1] neg_hi:[0,1]
	v_mov_b32_e32 v10, v16
	v_pk_add_f32 v[2:3], v[12:13], v[2:3] neg_lo:[0,1] neg_hi:[0,1]
	v_mov_b32_e32 v17, v5
	v_pk_add_f32 v[6:7], v[10:11], v[2:3]
	s_nop 0
	v_pk_add_f32 v[8:9], v[6:7], v[6:7] op_sel:[0,1] op_sel_hi:[1,0]
	s_nop 0
	v_pk_add_f32 v[4:5], v[4:5], v[8:9] op_sel:[1,0] op_sel_hi:[0,1]
	v_mov_b32_e32 v7, v4
	v_mov_b32_e32 v3, v8
	v_pk_add_f32 v[8:9], v[6:7], v[16:17] neg_lo:[0,1] neg_hi:[0,1]
	s_nop 0
	v_sub_f32_e32 v5, v6, v8
	v_pk_add_f32 v[2:3], v[2:3], v[8:9] neg_lo:[0,1] neg_hi:[0,1]
	v_sub_f32_e32 v5, v16, v5
	v_add_f32_e32 v2, v2, v5
	v_add_f32_e32 v2, v2, v3
	v_add_f32_e32 v2, v4, v2
	v_cndmask_b32_e32 v2, v121, v2, vcc
	v_cmp_lt_f32_e64 vcc, |v18|, s26
	s_nop 1
	v_cndmask_b32_e32 v34, v2, v18, vcc
	v_cmp_gt_f32_e32 vcc, s24, v20
	v_mul_f32_e32 v83, 0xbfb8aa3b, v34
	v_mul_f32_e32 v34, v83, v94
	v_subbrev_co_u32_e32 v10, vcc, 0, v21, vcc
	v_sub_u32_e32 v2, 0, v10
	v_ldexp_f32 v3, v19, v2
	v_add_f32_e32 v4, -1.0, v3
	v_add_f32_e32 v6, 1.0, v3
	v_add_f32_e32 v5, 1.0, v4
	v_add_f32_e32 v7, -1.0, v6
	v_ldexp_f32 v2, v22, v2
	v_sub_f32_e32 v5, v3, v5
	v_sub_f32_e32 v3, v3, v7
	v_add_f32_e32 v5, v2, v5
	v_add_f32_e32 v2, v2, v3
	v_add_f32_e32 v11, v6, v2
	v_rcp_f32_e32 v13, v11
	v_sub_f32_e32 v3, v6, v11
	v_add_f32_e32 v12, v2, v3
	v_add_f32_e32 v3, v4, v5
	v_mul_f32_e32 v15, v3, v13
	v_sub_f32_e32 v2, v4, v3
	v_mul_f32_e32 v4, v11, v15
	v_fma_f32 v6, v15, v11, -v4
	v_fmac_f32_e32 v6, v15, v12
	v_add_f32_e32 v14, v5, v2
	v_add_f32_e32 v2, v4, v6
	v_sub_f32_e32 v5, v3, v2
	v_pk_add_f32 v[8:9], v[2:3], v[4:5] neg_lo:[0,1] neg_hi:[0,1]
	v_mov_b32_e32 v7, v2
	v_pk_add_f32 v[2:3], v[8:9], v[6:7] neg_lo:[0,1] neg_hi:[0,1]
	v_cmp_neq_f32_e32 vcc, s11, v28
	v_add_f32_e32 v3, v14, v3
	v_add_f32_e32 v2, v2, v3
	v_add_f32_e32 v3, v5, v2
	v_mul_f32_e32 v14, v13, v3
	v_mul_f32_e32 v4, v11, v14
	v_fma_f32 v6, v14, v11, -v4
	v_fmac_f32_e32 v6, v14, v12
	v_sub_f32_e32 v5, v5, v3
	v_add_f32_e32 v11, v2, v5
	v_add_f32_e32 v2, v4, v6
	v_sub_f32_e32 v5, v3, v2
	v_pk_add_f32 v[8:9], v[2:3], v[4:5] neg_lo:[0,1] neg_hi:[0,1]
	v_mov_b32_e32 v7, v2
	v_pk_add_f32 v[2:3], v[8:9], v[6:7] neg_lo:[0,1] neg_hi:[0,1]
	v_add_f32_e32 v9, v15, v14
	v_add_f32_e32 v3, v11, v3
	v_add_f32_e32 v2, v2, v3
	v_add_f32_e32 v2, v5, v2
	v_sub_f32_e32 v3, v9, v15
	v_mul_f32_e32 v2, v13, v2
	v_sub_f32_e32 v3, v14, v3
	v_add_f32_e32 v11, v3, v2
	v_add_f32_e32 v12, v9, v11
	v_mul_f32_e32 v13, v12, v12
	v_fmamk_f32 v8, v13, 0x3e9b6dac, v120
	v_fmaak_f32 v87, v13, v8, 0x3f2aaada
	v_cvt_f32_i32_e32 v8, v10
	v_sub_f32_e32 v9, v12, v9
	v_sub_f32_e32 v9, v11, v9
	v_ldexp_f32 v14, v9, 1
	v_mul_f32_e32 v9, v12, v13
	v_ldexp_f32 v11, v12, 1
	v_pk_mul_f32 v[12:13], v[8:9], v[86:87]
	v_add_u32_e32 v2, s5, v1
	v_fma_f32 v10, v8, s25, -v12
	v_fmac_f32_e32 v10, 0xb102e308, v8
	v_pk_add_f32 v[8:9], v[12:13], v[10:11]
	v_mad_i64_i32 v[6:7], s[30:31], v2, s27, v[68:69]
	v_sub_f32_e32 v11, v9, v11
	v_sub_f32_e32 v11, v13, v11
	v_add_f32_e32 v15, v14, v11
	v_mov_b32_e32 v14, v12
	v_pk_add_f32 v[12:13], v[8:9], v[12:13] neg_lo:[0,1] neg_hi:[0,1]
	v_pk_add_f32 v[16:17], v[8:9], v[14:15]
	v_mov_b32_e32 v11, v8
	v_mov_b32_e32 v13, v17
	v_pk_add_f32 v[20:21], v[10:11], v[12:13]
	v_pk_add_f32 v[18:19], v[10:11], v[12:13] neg_lo:[0,1] neg_hi:[0,1]
	v_pk_add_f32 v[10:11], v[20:21], v[8:9] op_sel:[1,0] op_sel_hi:[0,1] neg_lo:[0,1] neg_hi:[0,1]
	v_pk_add_f32 v[12:13], v[16:17], v[10:11] op_sel_hi:[1,0] neg_lo:[0,1] neg_hi:[0,1]
	v_mov_b32_e32 v16, v17
	v_mov_b32_e32 v17, v21
	v_mov_b32_e32 v22, v9
	v_mov_b32_e32 v23, v10
	v_pk_add_f32 v[10:11], v[16:17], v[22:23] neg_lo:[0,1] neg_hi:[0,1]
	v_mov_b32_e32 v14, v15
	v_mov_b32_e32 v15, v8
	v_pk_add_f32 v[14:15], v[14:15], v[10:11] neg_lo:[0,1] neg_hi:[0,1]
	v_mov_b32_e32 v12, v18
	v_pk_add_f32 v[16:17], v[12:13], v[14:15]
	v_add_u32_e32 v10, s5, v90
	v_mad_i64_i32 v[22:23], s[30:31], v10, s27, v[68:69]
	v_pk_add_f32 v[24:25], v[16:17], v[16:17] op_sel:[0,1] op_sel_hi:[1,0]
	v_mov_b32_e32 v19, v21
	v_pk_add_f32 v[20:21], v[20:21], v[24:25] op_sel:[1,0] op_sel_hi:[0,1]
	v_mov_b32_e32 v17, v20
	v_pk_add_f32 v[26:27], v[16:17], v[18:19] neg_lo:[0,1] neg_hi:[0,1]
	v_mov_b32_e32 v15, v24
	v_sub_f32_e32 v16, v16, v26
	v_pk_add_f32 v[14:15], v[14:15], v[26:27] neg_lo:[0,1] neg_hi:[0,1]
	v_sub_f32_e32 v16, v18, v16
	v_add_f32_e32 v14, v14, v16
	v_add_f32_e32 v14, v14, v15
	v_add_f32_e32 v14, v20, v14
	v_cndmask_b32_e32 v14, v121, v14, vcc
	v_cmp_lt_f32_e64 vcc, |v28|, s26
	v_add_u32_e32 v18, s5, v91
	v_add_u32_e32 v26, s5, v92
	v_cndmask_b32_e32 v14, v14, v28, vcc
	v_mul_f32_e32 v81, 0xbfb8aa3b, v14
	v_mad_i64_i32 v[22:23], s[30:31], v18, s27, v[68:69]
	s_nop 0
	v_mad_i64_i32 v[30:31], s[30:31], v26, s27, v[68:69]
	s_nop 0
	s_waitcnt vmcnt(0)
	v_mov_b32_e32 v2, v184
	v_mov_b32_e32 v3, v185
	v_mov_b32_e32 v4, v186
	v_mov_b32_e32 v5, v187
	v_mov_b32_e32 v6, v188
	v_mov_b32_e32 v7, v189
	v_mov_b32_e32 v8, v190
	v_mov_b32_e32 v9, v191
	v_mov_b32_e32 v10, v192
	v_mov_b32_e32 v11, v193
	v_mov_b32_e32 v12, v194
	v_mov_b32_e32 v13, v195
	v_mov_b32_e32 v14, v196
	v_mov_b32_e32 v15, v197
	v_mov_b32_e32 v16, v198
	v_mov_b32_e32 v17, v199
	v_mov_b32_e32 v18, v200
	v_mov_b32_e32 v19, v201
	v_mov_b32_e32 v20, v202
	v_mov_b32_e32 v21, v203
	v_mov_b32_e32 v22, v204
	v_mov_b32_e32 v23, v205
	v_mov_b32_e32 v24, v206
	v_mov_b32_e32 v25, v207
	v_mov_b32_e32 v26, v208
	v_mov_b32_e32 v27, v209
	v_mov_b32_e32 v28, v210
	v_mov_b32_e32 v29, v211
	v_mov_b32_e32 v30, v216
	v_mov_b32_e32 v31, v217
	v_mov_b32_e32 v32, v218
	v_mov_b32_e32 v33, v219
	v_exp_f32_e32 v34, v34
	v_mul_f32_e32 v35, v81, v95
	v_exp_f32_e32 v37, v35
	s_barrier
	s_cselect_b32 s5, s28, 0x11000
	s_add_i32 s23, s5, 0
	s_and_b32 s5, s4, 0xc0
	s_add_i32 s23, s23, s5
	v_add3_u32 v79, s23, v93, v110
	s_add_i32 s29, s22, 0x1080
	v_mul_f32_e32 v85, v83, v112
	v_exp_f32_e32 v85, v85
	v_mul_f32_e32 v87, v81, v113
	v_exp_f32_e32 v87, v87
	s_lshl_b64 s[30:31], s[72:73], 16
	s_waitcnt vmcnt(7)
	v_lshlrev_b32_e32 v35, 16, v2
	v_and_b32_e32 v38, 0xffff0000, v2
	v_mul_f32_e32 v36, v34, v35
	v_mul_f32_e32 v2, v34, v38
	v_cvt_pk_bf16_f32 v2, v36, v2
	v_lshlrev_b32_e32 v36, 16, v3
	v_and_b32_e32 v40, 0xffff0000, v3
	v_mul_f32_e32 v39, v34, v36
	v_mul_f32_e32 v3, v34, v40
	v_cvt_pk_bf16_f32 v3, v39, v3
	v_lshlrev_b32_e32 v39, 16, v4
	v_and_b32_e32 v42, 0xffff0000, v4
	v_mul_f32_e32 v41, v34, v39
	v_mul_f32_e32 v4, v34, v42
	v_cvt_pk_bf16_f32 v4, v41, v4
	v_lshlrev_b32_e32 v41, 16, v5
	v_and_b32_e32 v44, 0xffff0000, v5
	v_mul_f32_e32 v43, v34, v41
	v_mul_f32_e32 v5, v34, v44
	v_mul_f32_e32 v34, v37, v35
	v_mul_f32_e32 v35, v37, v38
	v_cvt_pk_bf16_f32 v34, v34, v35
	v_mul_f32_e32 v35, v37, v36
	v_mul_f32_e32 v36, v37, v40
	v_cvt_pk_bf16_f32 v35, v35, v36
	v_mul_f32_e32 v36, v37, v39
	v_mul_f32_e32 v38, v37, v42
	v_cvt_pk_bf16_f32 v36, v36, v38
	v_mul_f32_e32 v38, v37, v41
	v_mul_f32_e32 v37, v37, v44
	v_cvt_pk_bf16_f32 v5, v43, v5
	v_cvt_pk_bf16_f32 v37, v38, v37
	s_waitcnt vmcnt(5)
	ds_write_b128 v96, v[6:9]
	ds_write_b128 v96, v[2:5] offset:34816
	ds_write_b128 v97, v[34:37]
	v_mul_f32_e32 v2, v83, v98
	v_exp_f32_e32 v5, v2
	v_mul_f32_e32 v2, v81, v99
	v_exp_f32_e32 v9, v2
	v_lshlrev_b32_e32 v6, 16, v10
	v_and_b32_e32 v7, 0xffff0000, v10
	v_mul_f32_e32 v2, v5, v6
	v_mul_f32_e32 v3, v5, v7
	v_lshlrev_b32_e32 v8, 16, v11
	v_and_b32_e32 v10, 0xffff0000, v11
	v_cvt_pk_bf16_f32 v2, v2, v3
	v_mul_f32_e32 v3, v5, v8
	v_mul_f32_e32 v4, v5, v10
	v_lshlrev_b32_e32 v11, 16, v12
	v_and_b32_e32 v12, 0xffff0000, v12
	v_mul_f32_e32 v6, v9, v6
	v_mul_f32_e32 v7, v9, v7
	v_cvt_pk_bf16_f32 v3, v3, v4
	v_mul_f32_e32 v4, v5, v11
	v_mul_f32_e32 v34, v5, v12
	v_cvt_pk_bf16_f32 v6, v6, v7
	v_mul_f32_e32 v7, v9, v8
	v_mul_f32_e32 v8, v9, v10
	v_cvt_pk_bf16_f32 v4, v4, v34
	v_lshlrev_b32_e32 v34, 16, v13
	v_and_b32_e32 v13, 0xffff0000, v13
	v_cvt_pk_bf16_f32 v7, v7, v8
	v_mul_f32_e32 v8, v9, v11
	v_mul_f32_e32 v10, v9, v12
	v_mul_f32_e32 v35, v5, v34
	v_mul_f32_e32 v5, v5, v13
	v_cvt_pk_bf16_f32 v8, v8, v10
	v_mul_f32_e32 v10, v9, v34
	v_mul_f32_e32 v9, v9, v13
	v_cvt_pk_bf16_f32 v5, v35, v5
	v_cvt_pk_bf16_f32 v9, v10, v9
	s_waitcnt vmcnt(4)
	ds_write_b128 v100, v[14:17]
	ds_write_b128 v100, v[2:5] offset:34816
	ds_write_b128 v101, v[6:9]
	v_mul_f32_e32 v2, v83, v102
	v_exp_f32_e32 v5, v2
	v_mul_f32_e32 v2, v81, v103
	v_exp_f32_e32 v9, v2
	s_waitcnt vmcnt(3)
	v_lshlrev_b32_e32 v6, 16, v18
	v_and_b32_e32 v7, 0xffff0000, v18
	v_mul_f32_e32 v2, v5, v6
	v_mul_f32_e32 v3, v5, v7
	v_lshlrev_b32_e32 v8, 16, v19
	v_and_b32_e32 v10, 0xffff0000, v19
	v_cvt_pk_bf16_f32 v2, v2, v3
	v_mul_f32_e32 v3, v5, v8
	v_mul_f32_e32 v4, v5, v10
	v_lshlrev_b32_e32 v11, 16, v20
	v_and_b32_e32 v12, 0xffff0000, v20
	v_mul_f32_e32 v6, v9, v6
	v_mul_f32_e32 v7, v9, v7
	v_cvt_pk_bf16_f32 v3, v3, v4
	v_mul_f32_e32 v4, v5, v11
	v_mul_f32_e32 v13, v5, v12
	v_cvt_pk_bf16_f32 v6, v6, v7
	v_mul_f32_e32 v7, v9, v8
	v_mul_f32_e32 v8, v9, v10
	v_cvt_pk_bf16_f32 v4, v4, v13
	v_lshlrev_b32_e32 v13, 16, v21
	v_and_b32_e32 v15, 0xffff0000, v21
	v_cvt_pk_bf16_f32 v7, v7, v8
	v_mul_f32_e32 v8, v9, v11
	v_mul_f32_e32 v10, v9, v12
	v_mul_f32_e32 v14, v5, v13
	v_mul_f32_e32 v5, v5, v15
	v_cvt_pk_bf16_f32 v8, v8, v10
	v_mul_f32_e32 v10, v9, v13
	v_mul_f32_e32 v9, v9, v15
	v_cvt_pk_bf16_f32 v5, v14, v5
	v_cvt_pk_bf16_f32 v9, v10, v9
	s_waitcnt vmcnt(2)
	ds_write_b128 v104, v[22:25]
	ds_write_b128 v104, v[2:5] offset:34816
	ds_write_b128 v105, v[6:9]
	v_mul_f32_e32 v2, v83, v106
	v_exp_f32_e32 v5, v2
	v_mul_f32_e32 v2, v81, v107
	v_exp_f32_e32 v9, v2
	s_waitcnt vmcnt(1)
	v_lshlrev_b32_e32 v6, 16, v26
	v_and_b32_e32 v7, 0xffff0000, v26
	v_mul_f32_e32 v2, v5, v6
	v_mul_f32_e32 v3, v5, v7
	v_lshlrev_b32_e32 v8, 16, v27
	v_and_b32_e32 v10, 0xffff0000, v27
	v_cvt_pk_bf16_f32 v2, v2, v3
	v_mul_f32_e32 v3, v5, v8
	v_mul_f32_e32 v4, v5, v10
	v_lshlrev_b32_e32 v11, 16, v28
	v_and_b32_e32 v12, 0xffff0000, v28
	v_mul_f32_e32 v6, v9, v6
	v_mul_f32_e32 v7, v9, v7
	v_cvt_pk_bf16_f32 v3, v3, v4
	v_mul_f32_e32 v4, v5, v11
	v_mul_f32_e32 v13, v5, v12
	v_cvt_pk_bf16_f32 v6, v6, v7
	v_mul_f32_e32 v7, v9, v8
	v_mul_f32_e32 v8, v9, v10
	v_cvt_pk_bf16_f32 v4, v4, v13
	v_lshlrev_b32_e32 v13, 16, v29
	v_and_b32_e32 v15, 0xffff0000, v29
	v_cvt_pk_bf16_f32 v7, v7, v8
	v_mul_f32_e32 v8, v9, v11
	v_mul_f32_e32 v10, v9, v12
	v_mul_f32_e32 v14, v5, v13
	v_mul_f32_e32 v5, v5, v15
	v_cvt_pk_bf16_f32 v8, v8, v10
	v_mul_f32_e32 v10, v9, v13
	v_mul_f32_e32 v9, v9, v15
	v_cvt_pk_bf16_f32 v5, v14, v5
	v_cvt_pk_bf16_f32 v9, v10, v9
	s_waitcnt vmcnt(0)
	ds_write_b128 v108, v[30:33]
	ds_write_b128 v108, v[2:5] offset:34816
	ds_write_b128 v109, v[6:9]
	s_waitcnt lgkmcnt(0)
	s_barrier
	ds_read_b64_tr_b16 v[4:5], v79 offset:1088
	ds_read_b64_tr_b16 v[2:3], v79
	ds_read_b64_tr_b16 v[8:9], v79 offset:1120
	ds_read_b64_tr_b16 v[6:7], v79 offset:32
	ds_read_b64_tr_b16 v[12:13], v111 offset:1088
	ds_read_b64_tr_b16 v[10:11], v111
	ds_read_b64_tr_b16 v[14:15], v111 offset:32
	ds_read_b64_tr_b16 v[18:19], v111 offset:64
	ds_read_b64_tr_b16 v[22:23], v111 offset:96
	ds_read_b64_tr_b16 v[16:17], v111 offset:1120
	ds_read_b64_tr_b16 v[20:21], v111 offset:1152
	ds_read_b64_tr_b16 v[24:25], v111 offset:1184
	ds_read_b64_tr_b16 v[44:45], v111 offset:1216
	ds_read_b64_tr_b16 v[42:43], v111 offset:128
	ds_read_b64_tr_b16 v[46:47], v111 offset:160
	ds_read_b64_tr_b16 v[50:51], v111 offset:192
	ds_read_b64_tr_b16 v[54:55], v111 offset:224
	ds_read_b64_tr_b16 v[48:49], v111 offset:1248
	ds_read_b64_tr_b16 v[52:53], v111 offset:1280
	ds_read_b64_tr_b16 v[56:57], v111 offset:1312
	s_waitcnt lgkmcnt(14)
	v_mfma_f32_16x16x32_bf16 v[26:29], v[2:5], v[10:13], 0
	v_mfma_f32_16x16x32_bf16 v[10:13], v[6:9], v[10:13], 0
	s_waitcnt lgkmcnt(10)
	v_mfma_f32_16x16x32_bf16 v[30:33], v[2:5], v[14:17], 0
	v_mfma_f32_16x16x32_bf16 v[14:17], v[6:9], v[14:17], 0
	s_waitcnt lgkmcnt(9)
	v_mfma_f32_16x16x32_bf16 v[34:37], v[2:5], v[18:21], 0
	v_mfma_f32_16x16x32_bf16 v[18:21], v[6:9], v[18:21], 0
	s_waitcnt lgkmcnt(8)
	v_mfma_f32_16x16x32_bf16 v[38:41], v[2:5], v[22:25], 0
	v_mfma_f32_16x16x32_bf16 v[22:25], v[6:9], v[22:25], 0
	s_waitcnt lgkmcnt(6)
	v_mfma_f32_16x16x32_bf16 v[58:61], v[2:5], v[42:45], 0
	v_mfma_f32_16x16x32_bf16 v[42:45], v[6:9], v[42:45], 0
	s_waitcnt lgkmcnt(2)
	v_mfma_f32_16x16x32_bf16 v[62:65], v[2:5], v[46:49], 0
	v_mfma_f32_16x16x32_bf16 v[46:49], v[6:9], v[46:49], 0
	s_waitcnt lgkmcnt(1)
	v_mfma_f32_16x16x32_bf16 v[122:125], v[2:5], v[50:53], 0
	v_mfma_f32_16x16x32_bf16 v[50:53], v[6:9], v[50:53], 0
	s_waitcnt lgkmcnt(0)
	v_mfma_f32_16x16x32_bf16 v[2:5], v[2:5], v[54:57], 0
	v_mfma_f32_16x16x32_bf16 v[6:9], v[6:9], v[54:57], 0
	ds_read_b64_tr_b16 v[54:55], v79 offset:8704
	ds_read_b64_tr_b16 v[56:57], v79 offset:9792
	ds_read_b64_tr_b16 v[128:129], v79 offset:9824
	ds_read_b64_tr_b16 v[126:127], v79 offset:8736
	ds_read_b64_tr_b16 v[138:139], v111 offset:9792
	ds_read_b64_tr_b16 v[136:137], v111 offset:8704
	ds_read_b64_tr_b16 v[142:143], v111 offset:8736
	ds_read_b64_tr_b16 v[146:147], v111 offset:8768
	ds_read_b64_tr_b16 v[150:151], v111 offset:8800
	ds_read_b64_tr_b16 v[144:145], v111 offset:9824
	ds_read_b64_tr_b16 v[148:149], v111 offset:9856
	ds_read_b64_tr_b16 v[152:153], v111 offset:9888
	s_waitcnt lgkmcnt(6)
	v_mfma_f32_16x16x32_bf16 v[26:29], v[54:57], v[136:139], v[26:29]
	v_mfma_f32_16x16x32_bf16 v[10:13], v[126:129], v[136:139], v[10:13]
	s_waitcnt lgkmcnt(2)
	v_mfma_f32_16x16x32_bf16 v[30:33], v[54:57], v[142:145], v[30:33]
	v_mfma_f32_16x16x32_bf16 v[14:17], v[126:129], v[142:145], v[14:17]
	s_waitcnt lgkmcnt(1)
	v_mfma_f32_16x16x32_bf16 v[34:37], v[54:57], v[146:149], v[34:37]
	v_mfma_f32_16x16x32_bf16 v[18:21], v[126:129], v[146:149], v[18:21]
	s_waitcnt lgkmcnt(0)
	v_mfma_f32_16x16x32_bf16 v[38:41], v[54:57], v[150:153], v[38:41]
	v_mfma_f32_16x16x32_bf16 v[22:25], v[126:129], v[150:153], v[22:25]
	ds_read_b64_tr_b16 v[138:139], v111 offset:9920
	ds_read_b64_tr_b16 v[136:137], v111 offset:8832
	ds_read_b64_tr_b16 v[142:143], v111 offset:8864
	ds_read_b64_tr_b16 v[146:147], v111 offset:8896
	ds_read_b64_tr_b16 v[150:151], v111 offset:8928
	ds_read_b64_tr_b16 v[144:145], v111 offset:9952
	ds_read_b64_tr_b16 v[148:149], v111 offset:9984
	ds_read_b64_tr_b16 v[152:153], v111 offset:10016
	s_waitcnt lgkmcnt(6)
	v_mfma_f32_16x16x32_bf16 v[58:61], v[54:57], v[136:139], v[58:61]
	v_mfma_f32_16x16x32_bf16 v[42:45], v[126:129], v[136:139], v[42:45]
	s_waitcnt lgkmcnt(2)
	v_mfma_f32_16x16x32_bf16 v[62:65], v[54:57], v[142:145], v[62:65]
	v_mfma_f32_16x16x32_bf16 v[46:49], v[126:129], v[142:145], v[46:49]
	s_waitcnt lgkmcnt(1)
	v_mfma_f32_16x16x32_bf16 v[122:125], v[54:57], v[146:149], v[122:125]
	v_mfma_f32_16x16x32_bf16 v[50:53], v[126:129], v[146:149], v[50:53]
	s_waitcnt lgkmcnt(0)
	v_mfma_f32_16x16x32_bf16 v[2:5], v[54:57], v[150:153], v[2:5]
	v_mfma_f32_16x16x32_bf16 v[6:9], v[126:129], v[150:153], v[6:9]
	ds_read_b64_tr_b16 v[54:55], v79 offset:17408
	ds_read_b64_tr_b16 v[56:57], v79 offset:18496
	ds_read_b64_tr_b16 v[128:129], v79 offset:18528
	ds_read_b64_tr_b16 v[126:127], v79 offset:17440
	ds_read_b64_tr_b16 v[138:139], v111 offset:18496
	ds_read_b64_tr_b16 v[136:137], v111 offset:17408
	ds_read_b64_tr_b16 v[142:143], v111 offset:17440
	ds_read_b64_tr_b16 v[146:147], v111 offset:17472
	ds_read_b64_tr_b16 v[150:151], v111 offset:17504
	ds_read_b64_tr_b16 v[144:145], v111 offset:18528
	ds_read_b64_tr_b16 v[148:149], v111 offset:18560
	ds_read_b64_tr_b16 v[152:153], v111 offset:18592
	s_waitcnt lgkmcnt(6)
	v_mfma_f32_16x16x32_bf16 v[26:29], v[54:57], v[136:139], v[26:29]
	v_mfma_f32_16x16x32_bf16 v[10:13], v[126:129], v[136:139], v[10:13]
	s_waitcnt lgkmcnt(2)
	v_mfma_f32_16x16x32_bf16 v[30:33], v[54:57], v[142:145], v[30:33]
	v_mfma_f32_16x16x32_bf16 v[14:17], v[126:129], v[142:145], v[14:17]
	s_waitcnt lgkmcnt(1)
	v_mfma_f32_16x16x32_bf16 v[34:37], v[54:57], v[146:149], v[34:37]
	v_mfma_f32_16x16x32_bf16 v[136:139], v[126:129], v[146:149], v[18:21]
	s_waitcnt lgkmcnt(0)
	v_mfma_f32_16x16x32_bf16 v[38:41], v[54:57], v[150:153], v[38:41]
	v_mfma_f32_16x16x32_bf16 v[142:145], v[126:129], v[150:153], v[22:25]
	ds_read_b64_tr_b16 v[20:21], v111 offset:18624
	ds_read_b64_tr_b16 v[18:19], v111 offset:17536
	s_nop 0
	ds_read_b64_tr_b16 v[22:23], v111 offset:17568
	ds_read_b64_tr_b16 v[146:147], v111 offset:17600
	ds_read_b64_tr_b16 v[150:151], v111 offset:17632
	ds_read_b64_tr_b16 v[24:25], v111 offset:18656
	ds_read_b64_tr_b16 v[148:149], v111 offset:18688
	ds_read_b64_tr_b16 v[152:153], v111 offset:18720
	s_waitcnt lgkmcnt(6)
	v_mfma_f32_16x16x32_bf16 v[58:61], v[54:57], v[18:21], v[58:61]
	v_mfma_f32_16x16x32_bf16 v[42:45], v[126:129], v[18:21], v[42:45]
	s_waitcnt lgkmcnt(2)
	v_mfma_f32_16x16x32_bf16 v[62:65], v[54:57], v[22:25], v[62:65]
	v_mfma_f32_16x16x32_bf16 v[46:49], v[126:129], v[22:25], v[46:49]
	s_waitcnt lgkmcnt(1)
	v_mfma_f32_16x16x32_bf16 v[122:125], v[54:57], v[146:149], v[122:125]
	v_mfma_f32_16x16x32_bf16 v[146:149], v[126:129], v[146:149], v[50:53]
	s_waitcnt lgkmcnt(0)
	v_mfma_f32_16x16x32_bf16 v[154:157], v[54:57], v[150:153], v[2:5]
	v_mfma_f32_16x16x32_bf16 v[126:129], v[126:129], v[150:153], v[6:9]
	ds_read_b64_tr_b16 v[150:151], v79 offset:26112
	ds_read_b64_tr_b16 v[152:153], v79 offset:27200
	ds_read_b64_tr_b16 v[160:161], v79 offset:27232
	ds_read_b64_tr_b16 v[158:159], v79 offset:26144
	ds_read_b64_tr_b16 v[8:9], v111 offset:27200
	ds_read_b64_tr_b16 v[6:7], v111 offset:26112
	ds_read_b64_tr_b16 v[18:19], v111 offset:26144
	ds_read_b64_tr_b16 v[22:23], v111 offset:26176
	ds_read_b64_tr_b16 v[50:51], v111 offset:26208
	ds_read_b64_tr_b16 v[20:21], v111 offset:27232
	ds_read_b64_tr_b16 v[24:25], v111 offset:27264
	ds_read_b64_tr_b16 v[52:53], v111 offset:27296
	s_waitcnt lgkmcnt(6)
	v_mfma_f32_16x16x32_bf16 v[2:5], v[150:153], v[6:9], v[26:29]
	v_mfma_f32_16x16x32_bf16 v[6:9], v[158:161], v[6:9], v[10:13]
	s_waitcnt lgkmcnt(2)
	v_mfma_f32_16x16x32_bf16 v[10:13], v[150:153], v[18:21], v[30:33]
	v_mfma_f32_16x16x32_bf16 v[14:17], v[158:161], v[18:21], v[14:17]
	s_waitcnt lgkmcnt(1)
	v_mfma_f32_16x16x32_bf16 v[18:21], v[150:153], v[22:25], v[34:37]
	v_mfma_f32_16x16x32_bf16 v[22:25], v[158:161], v[22:25], v[136:139]
	s_waitcnt lgkmcnt(0)
	v_mfma_f32_16x16x32_bf16 v[26:29], v[150:153], v[50:53], v[38:41]
	v_mfma_f32_16x16x32_bf16 v[30:33], v[158:161], v[50:53], v[142:145]
	s_nop 1
	ds_read_b64_tr_b16 v[40:41], v111 offset:27328
	ds_read_b64_tr_b16 v[38:39], v111 offset:26240
	ds_read_b64_tr_b16 v[50:51], v111 offset:26272
	ds_read_b64_tr_b16 v[54:55], v111 offset:26304
	ds_read_b64_tr_b16 v[136:137], v111 offset:26336
	ds_read_b64_tr_b16 v[52:53], v111 offset:27360
	ds_read_b64_tr_b16 v[56:57], v111 offset:27392
	ds_read_b64_tr_b16 v[138:139], v111 offset:27424
	s_waitcnt lgkmcnt(6)
	v_mfma_f32_16x16x32_bf16 v[34:37], v[150:153], v[38:41], v[58:61]
	s_nop 2
	v_add_u32_e32 v58, s29, v1
	v_mad_i64_i32 v[58:59], s[22:23], v58, s27, v[68:69]
	global_load_dwordx4 v[142:145], v[58:59], off offset:1024
	global_load_dwordx4 v[162:165], v[58:59], off offset:2048
	v_add_u32_e32 v58, s29, v90
	v_mad_i64_i32 v[58:59], s[22:23], v58, s27, v[68:69]
	global_load_dwordx4 v[166:169], v[58:59], off offset:1024
	global_load_dwordx4 v[170:173], v[58:59], off offset:2048
	v_mfma_f32_16x16x32_bf16 v[38:41], v[158:161], v[38:41], v[42:45]
	v_add_u32_e32 v58, s29, v92
	v_mad_i64_i32 v[58:59], s[22:23], v58, s27, v[68:69]
	s_waitcnt lgkmcnt(2)
	v_mfma_f32_16x16x32_bf16 v[42:45], v[150:153], v[50:53], v[62:65]
	s_waitcnt vmcnt(3)
	v_lshlrev_b32_e32 v131, 16, v142
	s_nop 0
	v_add_u32_e32 v62, s29, v91
	v_mad_i64_i32 v[62:63], s[22:23], v62, s27, v[68:69]
	v_mfma_f32_16x16x32_bf16 v[46:49], v[158:161], v[50:53], v[46:49]
	v_and_b32_e32 v132, 0xffff0000, v142
	v_lshlrev_b32_e32 v133, 16, v143
	v_and_b32_e32 v134, 0xffff0000, v143
	s_waitcnt lgkmcnt(1)
	v_mfma_f32_16x16x32_bf16 v[50:53], v[150:153], v[54:57], v[122:125]
	v_lshlrev_b32_e32 v140, 16, v145
	v_and_b32_e32 v142, 0xffff0000, v145
	s_ashr_i32 s22, s4, 8
	v_mfma_f32_16x16x32_bf16 v[54:57], v[158:161], v[54:57], v[146:149]
	global_load_dwordx4 v[122:125], v[58:59], off offset:2048
	s_nop 1
	global_load_dwordx4 v[146:149], v[58:59], off offset:1024
	s_ashr_i32 s23, s22, 31
	s_add_u32 s4, s92, s30
	s_waitcnt lgkmcnt(0)
	v_mfma_f32_16x16x32_bf16 v[58:61], v[150:153], v[136:139], v[154:157]
	global_load_dwordx4 v[150:153], v[62:63], off offset:2048
	s_nop 1
	global_load_dwordx4 v[154:157], v[62:63], off offset:1024
	s_barrier
	v_mfma_f32_16x16x32_bf16 v[62:65], v[158:161], v[136:139], v[126:129]
	v_lshlrev_b32_e32 v138, 16, v144
	v_and_b32_e32 v139, 0xffff0000, v144
	s_nop 0
	v_mul_f32_e32 v126, v85, v131
	v_mul_f32_e32 v127, v85, v132
	v_cvt_pk_bf16_f32 v126, v126, v127
	v_mul_f32_e32 v127, v85, v133
	v_mul_f32_e32 v128, v85, v134
	v_cvt_pk_bf16_f32 v127, v127, v128
	v_mul_f32_e32 v128, v85, v138
	v_mul_f32_e32 v129, v85, v139
	v_cvt_pk_bf16_f32 v128, v128, v129
	v_mul_f32_e32 v129, v85, v140
	v_mul_f32_e32 v85, v85, v142
	v_cvt_pk_bf16_f32 v129, v129, v85
	v_mul_f32_e32 v85, v87, v131
	v_mul_f32_e32 v131, v87, v132
	v_cvt_pk_bf16_f32 v136, v85, v131
	v_mul_f32_e32 v85, v87, v133
	v_mul_f32_e32 v131, v87, v134
	v_cvt_pk_bf16_f32 v137, v85, v131
	v_mul_f32_e32 v85, v87, v138
	v_mul_f32_e32 v131, v87, v139
	v_cvt_pk_bf16_f32 v138, v85, v131
	v_mul_f32_e32 v85, v87, v140
	v_mul_f32_e32 v87, v87, v142
	v_cvt_pk_bf16_f32 v139, v85, v87
	v_mul_f32_e32 v85, v83, v114
	v_exp_f32_e32 v85, v85
	v_mul_f32_e32 v87, v81, v115
	s_waitcnt vmcnt(5)
	v_lshlrev_b32_e32 v131, 16, v166
	v_and_b32_e32 v132, 0xffff0000, v166
	ds_write_b128 v96, v[162:165]
	ds_write_b128 v96, v[126:129] offset:34816
	ds_write_b128 v97, v[136:139]
	v_exp_f32_e32 v87, v87
	v_mul_f32_e32 v126, v85, v131
	v_mul_f32_e32 v127, v85, v132
	v_lshlrev_b32_e32 v133, 16, v167
	v_and_b32_e32 v134, 0xffff0000, v167
	v_cvt_pk_bf16_f32 v126, v126, v127
	v_mul_f32_e32 v127, v85, v133
	v_mul_f32_e32 v128, v85, v134
	v_lshlrev_b32_e32 v138, 16, v168
	v_and_b32_e32 v139, 0xffff0000, v168
	v_cvt_pk_bf16_f32 v127, v127, v128
	v_mul_f32_e32 v128, v85, v138
	v_mul_f32_e32 v129, v85, v139
	v_lshlrev_b32_e32 v140, 16, v169
	v_and_b32_e32 v142, 0xffff0000, v169
	v_cvt_pk_bf16_f32 v128, v128, v129
	v_mul_f32_e32 v129, v85, v140
	v_mul_f32_e32 v85, v85, v142
	v_cvt_pk_bf16_f32 v129, v129, v85
	v_mul_f32_e32 v85, v87, v131
	v_mul_f32_e32 v131, v87, v132
	v_cvt_pk_bf16_f32 v136, v85, v131
	v_mul_f32_e32 v85, v87, v133
	v_mul_f32_e32 v131, v87, v134
	v_cvt_pk_bf16_f32 v137, v85, v131
	v_mul_f32_e32 v85, v87, v138
	v_mul_f32_e32 v131, v87, v139
	v_cvt_pk_bf16_f32 v138, v85, v131
	v_mul_f32_e32 v85, v87, v140
	v_mul_f32_e32 v87, v87, v142
	v_cvt_pk_bf16_f32 v139, v85, v87
	v_mul_f32_e32 v85, v83, v116
	v_exp_f32_e32 v85, v85
	v_mul_f32_e32 v87, v81, v117
	s_waitcnt vmcnt(4)
	ds_write_b128 v100, v[170:173]
	ds_write_b128 v100, v[126:129] offset:34816
	ds_write_b128 v101, v[136:139]
	v_exp_f32_e32 v87, v87
	v_mul_f32_e32 v83, v83, v118
	v_exp_f32_e32 v83, v83
	v_mul_f32_e32 v81, v81, v119
	v_exp_f32_e32 v81, v81
	s_addc_u32 s29, s93, s31
	s_lshl_b64 s[22:23], s[22:23], 15
	s_add_u32 s4, s4, s22
	s_waitcnt vmcnt(0)
	v_lshlrev_b32_e32 v131, 16, v154
	v_and_b32_e32 v132, 0xffff0000, v154
	v_mul_f32_e32 v126, v85, v131
	v_mul_f32_e32 v127, v85, v132
	v_lshlrev_b32_e32 v133, 16, v155
	v_and_b32_e32 v134, 0xffff0000, v155
	v_cvt_pk_bf16_f32 v126, v126, v127
	v_mul_f32_e32 v127, v85, v133
	v_mul_f32_e32 v128, v85, v134
	v_lshlrev_b32_e32 v138, 16, v156
	v_and_b32_e32 v139, 0xffff0000, v156
	v_cvt_pk_bf16_f32 v127, v127, v128
	v_mul_f32_e32 v128, v85, v138
	v_mul_f32_e32 v129, v85, v139
	v_lshlrev_b32_e32 v140, 16, v157
	v_and_b32_e32 v142, 0xffff0000, v157
	v_cvt_pk_bf16_f32 v128, v128, v129
	v_mul_f32_e32 v129, v85, v140
	v_mul_f32_e32 v85, v85, v142
	v_cvt_pk_bf16_f32 v129, v129, v85
	v_mul_f32_e32 v85, v87, v131
	v_mul_f32_e32 v131, v87, v132
	v_cvt_pk_bf16_f32 v136, v85, v131
	v_mul_f32_e32 v85, v87, v133
	v_mul_f32_e32 v131, v87, v134
	v_cvt_pk_bf16_f32 v137, v85, v131
	v_mul_f32_e32 v85, v87, v138
	v_mul_f32_e32 v131, v87, v139
	v_cvt_pk_bf16_f32 v138, v85, v131
	v_mul_f32_e32 v85, v87, v140
	v_mul_f32_e32 v87, v87, v142
	v_cvt_pk_bf16_f32 v139, v85, v87
	v_lshlrev_b32_e32 v85, 16, v146
	v_and_b32_e32 v131, 0xffff0000, v146
	ds_write_b128 v104, v[150:153]
	ds_write_b128 v104, v[126:129] offset:34816
	ds_write_b128 v105, v[136:139]
	v_mul_f32_e32 v87, v83, v85
	v_mul_f32_e32 v126, v83, v131
	v_cvt_pk_bf16_f32 v126, v87, v126
	v_lshlrev_b32_e32 v87, 16, v147
	v_and_b32_e32 v132, 0xffff0000, v147
	v_mul_f32_e32 v127, v83, v87
	v_mul_f32_e32 v128, v83, v132
	v_lshlrev_b32_e32 v133, 16, v148
	v_and_b32_e32 v134, 0xffff0000, v148
	v_cvt_pk_bf16_f32 v127, v127, v128
	v_mul_f32_e32 v128, v83, v133
	v_mul_f32_e32 v129, v83, v134
	v_lshlrev_b32_e32 v139, 16, v149
	v_and_b32_e32 v140, 0xffff0000, v149
	v_cvt_pk_bf16_f32 v128, v128, v129
	v_mul_f32_e32 v129, v83, v139
	v_mul_f32_e32 v83, v83, v140
	v_cvt_pk_bf16_f32 v129, v129, v83
	v_mul_f32_e32 v83, v81, v85
	v_mul_f32_e32 v85, v81, v131
	v_cvt_pk_bf16_f32 v136, v83, v85
	v_mul_f32_e32 v83, v81, v87
	v_mul_f32_e32 v85, v81, v132
	v_cvt_pk_bf16_f32 v137, v83, v85
	v_mul_f32_e32 v83, v81, v133
	v_mul_f32_e32 v85, v81, v134
	v_cvt_pk_bf16_f32 v138, v83, v85
	v_mul_f32_e32 v83, v81, v139
	v_mul_f32_e32 v81, v81, v140
	v_cvt_pk_bf16_f32 v139, v83, v81
	ds_write_b128 v108, v[122:125]
	ds_write_b128 v108, v[126:129] offset:34816
	ds_write_b128 v109, v[136:139]
	s_waitcnt lgkmcnt(0)
	s_barrier
	ds_read_b64_tr_b16 v[124:125], v79 offset:1088
	ds_read_b64_tr_b16 v[122:123], v79
	ds_read_b64_tr_b16 v[128:129], v79 offset:1120
	ds_read_b64_tr_b16 v[126:127], v79 offset:32
	ds_read_b64_tr_b16 v[138:139], v111 offset:1088
	ds_read_b64_tr_b16 v[136:137], v111
	ds_read_b64_tr_b16 v[142:143], v111 offset:32
	ds_read_b64_tr_b16 v[146:147], v111 offset:64
	ds_read_b64_tr_b16 v[150:151], v111 offset:96
	ds_read_b64_tr_b16 v[144:145], v111 offset:1120
	ds_read_b64_tr_b16 v[148:149], v111 offset:1152
	ds_read_b64_tr_b16 v[152:153], v111 offset:1184
	s_waitcnt lgkmcnt(6)
	v_mfma_f32_16x16x32_bf16 v[2:5], v[122:125], v[136:139], v[2:5]
	s_addc_u32 s22, s29, s23
	s_add_u32 s4, s4, s5
	s_addc_u32 s5, s22, 0
	v_mfma_f32_16x16x32_bf16 v[6:9], v[126:129], v[136:139], v[6:9]
	v_mov_b32_e32 v81, v67
	v_mov_b32_e32 v83, v67
	v_mov_b32_e32 v85, v67
	s_waitcnt lgkmcnt(2)
	v_mfma_f32_16x16x32_bf16 v[10:13], v[122:125], v[142:145], v[10:13]
	v_mfma_f32_16x16x32_bf16 v[14:17], v[126:129], v[142:145], v[14:17]
	s_waitcnt lgkmcnt(1)
	v_mfma_f32_16x16x32_bf16 v[18:21], v[122:125], v[146:149], v[18:21]
	v_mfma_f32_16x16x32_bf16 v[22:25], v[126:129], v[146:149], v[22:25]
	s_waitcnt lgkmcnt(0)
	v_mfma_f32_16x16x32_bf16 v[26:29], v[122:125], v[150:153], v[26:29]
	v_mfma_f32_16x16x32_bf16 v[30:33], v[126:129], v[150:153], v[30:33]
	ds_read_b64_tr_b16 v[138:139], v111 offset:1216
	ds_read_b64_tr_b16 v[136:137], v111 offset:128
	ds_read_b64_tr_b16 v[142:143], v111 offset:160
	ds_read_b64_tr_b16 v[146:147], v111 offset:192
	ds_read_b64_tr_b16 v[150:151], v111 offset:224
	ds_read_b64_tr_b16 v[144:145], v111 offset:1248
	ds_read_b64_tr_b16 v[148:149], v111 offset:1280
	ds_read_b64_tr_b16 v[152:153], v111 offset:1312
	s_waitcnt lgkmcnt(6)
	v_mfma_f32_16x16x32_bf16 v[34:37], v[122:125], v[136:139], v[34:37]
	v_mfma_f32_16x16x32_bf16 v[38:41], v[126:129], v[136:139], v[38:41]
	s_waitcnt lgkmcnt(2)
	v_mfma_f32_16x16x32_bf16 v[42:45], v[122:125], v[142:145], v[42:45]
	v_mfma_f32_16x16x32_bf16 v[46:49], v[126:129], v[142:145], v[46:49]
	s_waitcnt lgkmcnt(1)
	v_mfma_f32_16x16x32_bf16 v[50:53], v[122:125], v[146:149], v[50:53]
	v_mfma_f32_16x16x32_bf16 v[54:57], v[126:129], v[146:149], v[54:57]
	s_waitcnt lgkmcnt(0)
	v_mfma_f32_16x16x32_bf16 v[58:61], v[122:125], v[150:153], v[58:61]
	v_mfma_f32_16x16x32_bf16 v[62:65], v[126:129], v[150:153], v[62:65]
	ds_read_b64_tr_b16 v[122:123], v79 offset:8704
	ds_read_b64_tr_b16 v[124:125], v79 offset:9792
	ds_read_b64_tr_b16 v[128:129], v79 offset:9824
	ds_read_b64_tr_b16 v[126:127], v79 offset:8736
	ds_read_b64_tr_b16 v[138:139], v111 offset:9792
	ds_read_b64_tr_b16 v[136:137], v111 offset:8704
	ds_read_b64_tr_b16 v[142:143], v111 offset:8736
	ds_read_b64_tr_b16 v[146:147], v111 offset:8768
	ds_read_b64_tr_b16 v[150:151], v111 offset:8800
	ds_read_b64_tr_b16 v[144:145], v111 offset:9824
	ds_read_b64_tr_b16 v[148:149], v111 offset:9856
	ds_read_b64_tr_b16 v[152:153], v111 offset:9888
	s_waitcnt lgkmcnt(6)
	v_mfma_f32_16x16x32_bf16 v[2:5], v[122:125], v[136:139], v[2:5]
	v_mfma_f32_16x16x32_bf16 v[6:9], v[126:129], v[136:139], v[6:9]
	s_waitcnt lgkmcnt(2)
	v_mfma_f32_16x16x32_bf16 v[10:13], v[122:125], v[142:145], v[10:13]
	v_mfma_f32_16x16x32_bf16 v[14:17], v[126:129], v[142:145], v[14:17]
	s_waitcnt lgkmcnt(1)
	v_mfma_f32_16x16x32_bf16 v[18:21], v[122:125], v[146:149], v[18:21]
	v_mfma_f32_16x16x32_bf16 v[22:25], v[126:129], v[146:149], v[22:25]
	s_waitcnt lgkmcnt(0)
	v_mfma_f32_16x16x32_bf16 v[26:29], v[122:125], v[150:153], v[26:29]
	v_mfma_f32_16x16x32_bf16 v[30:33], v[126:129], v[150:153], v[30:33]
	ds_read_b64_tr_b16 v[138:139], v111 offset:9920
	ds_read_b64_tr_b16 v[136:137], v111 offset:8832
	ds_read_b64_tr_b16 v[142:143], v111 offset:8864
	ds_read_b64_tr_b16 v[146:147], v111 offset:8896
	ds_read_b64_tr_b16 v[150:151], v111 offset:8928
	ds_read_b64_tr_b16 v[144:145], v111 offset:9952
	ds_read_b64_tr_b16 v[148:149], v111 offset:9984
	ds_read_b64_tr_b16 v[152:153], v111 offset:10016
	s_waitcnt lgkmcnt(6)
	v_mfma_f32_16x16x32_bf16 v[34:37], v[122:125], v[136:139], v[34:37]
	v_mfma_f32_16x16x32_bf16 v[38:41], v[126:129], v[136:139], v[38:41]
	s_waitcnt lgkmcnt(2)
	v_mfma_f32_16x16x32_bf16 v[42:45], v[122:125], v[142:145], v[42:45]
	v_mfma_f32_16x16x32_bf16 v[46:49], v[126:129], v[142:145], v[46:49]
	s_waitcnt lgkmcnt(1)
	v_mfma_f32_16x16x32_bf16 v[50:53], v[122:125], v[146:149], v[50:53]
	v_mfma_f32_16x16x32_bf16 v[54:57], v[126:129], v[146:149], v[54:57]
	s_waitcnt lgkmcnt(0)
	v_mfma_f32_16x16x32_bf16 v[58:61], v[122:125], v[150:153], v[58:61]
	v_mfma_f32_16x16x32_bf16 v[62:65], v[126:129], v[150:153], v[62:65]
	ds_read_b64_tr_b16 v[122:123], v79 offset:17408
	ds_read_b64_tr_b16 v[124:125], v79 offset:18496
	ds_read_b64_tr_b16 v[128:129], v79 offset:18528
	ds_read_b64_tr_b16 v[126:127], v79 offset:17440
	ds_read_b64_tr_b16 v[138:139], v111 offset:18496
	ds_read_b64_tr_b16 v[136:137], v111 offset:17408
	ds_read_b64_tr_b16 v[142:143], v111 offset:17440
	ds_read_b64_tr_b16 v[146:147], v111 offset:17472
	ds_read_b64_tr_b16 v[150:151], v111 offset:17504
	ds_read_b64_tr_b16 v[144:145], v111 offset:18528
	ds_read_b64_tr_b16 v[148:149], v111 offset:18560
	ds_read_b64_tr_b16 v[152:153], v111 offset:18592
	s_waitcnt lgkmcnt(6)
	v_mfma_f32_16x16x32_bf16 v[2:5], v[122:125], v[136:139], v[2:5]
	v_mfma_f32_16x16x32_bf16 v[6:9], v[126:129], v[136:139], v[6:9]
	s_waitcnt lgkmcnt(2)
	v_mfma_f32_16x16x32_bf16 v[10:13], v[122:125], v[142:145], v[10:13]
	v_mfma_f32_16x16x32_bf16 v[14:17], v[126:129], v[142:145], v[14:17]
	s_waitcnt lgkmcnt(1)
	v_mfma_f32_16x16x32_bf16 v[18:21], v[122:125], v[146:149], v[18:21]
	v_mfma_f32_16x16x32_bf16 v[22:25], v[126:129], v[146:149], v[22:25]
	s_waitcnt lgkmcnt(0)
	v_mfma_f32_16x16x32_bf16 v[26:29], v[122:125], v[150:153], v[26:29]
	v_mfma_f32_16x16x32_bf16 v[30:33], v[126:129], v[150:153], v[30:33]
	ds_read_b64_tr_b16 v[138:139], v111 offset:18624
	ds_read_b64_tr_b16 v[136:137], v111 offset:17536
	ds_read_b64_tr_b16 v[142:143], v111 offset:17568
	ds_read_b64_tr_b16 v[146:147], v111 offset:17600
	ds_read_b64_tr_b16 v[150:151], v111 offset:17632
	ds_read_b64_tr_b16 v[144:145], v111 offset:18656
	ds_read_b64_tr_b16 v[148:149], v111 offset:18688
	ds_read_b64_tr_b16 v[152:153], v111 offset:18720
	s_waitcnt lgkmcnt(6)
	v_mfma_f32_16x16x32_bf16 v[34:37], v[122:125], v[136:139], v[34:37]
	v_mfma_f32_16x16x32_bf16 v[38:41], v[126:129], v[136:139], v[38:41]
	s_waitcnt lgkmcnt(2)
	v_mfma_f32_16x16x32_bf16 v[42:45], v[122:125], v[142:145], v[42:45]
	v_mfma_f32_16x16x32_bf16 v[46:49], v[126:129], v[142:145], v[46:49]
	s_waitcnt lgkmcnt(1)
	v_mfma_f32_16x16x32_bf16 v[50:53], v[122:125], v[146:149], v[50:53]
	v_mfma_f32_16x16x32_bf16 v[54:57], v[126:129], v[146:149], v[54:57]
	s_waitcnt lgkmcnt(0)
	v_mfma_f32_16x16x32_bf16 v[58:61], v[122:125], v[150:153], v[58:61]
	v_mfma_f32_16x16x32_bf16 v[62:65], v[126:129], v[150:153], v[62:65]
	ds_read_b64_tr_b16 v[122:123], v79 offset:26112
	ds_read_b64_tr_b16 v[124:125], v79 offset:27200
	ds_read_b64_tr_b16 v[128:129], v79 offset:27232
	ds_read_b64_tr_b16 v[126:127], v79 offset:26144
	ds_read_b64_tr_b16 v[138:139], v111 offset:27200
	ds_read_b64_tr_b16 v[136:137], v111 offset:26112
	ds_read_b64_tr_b16 v[142:143], v111 offset:26144
	ds_read_b64_tr_b16 v[146:147], v111 offset:26176
	ds_read_b64_tr_b16 v[150:151], v111 offset:26208
	ds_read_b64_tr_b16 v[144:145], v111 offset:27232
	ds_read_b64_tr_b16 v[148:149], v111 offset:27264
	ds_read_b64_tr_b16 v[152:153], v111 offset:27296
	v_mov_b32_e32 v79, v67
	s_waitcnt lgkmcnt(6)
	v_mfma_f32_16x16x32_bf16 v[2:5], v[122:125], v[136:139], v[2:5]
	v_mfma_f32_16x16x32_bf16 v[6:9], v[126:129], v[136:139], v[6:9]
	s_waitcnt lgkmcnt(2)
	v_mfma_f32_16x16x32_bf16 v[10:13], v[122:125], v[142:145], v[10:13]
	s_nop 4
	v_cvt_pk_bf16_f32 v2, v2, v3
	v_cvt_pk_bf16_f32 v3, v4, v5
	v_cvt_pk_bf16_f32 v6, v6, v7
	v_mfma_f32_16x16x32_bf16 v[14:17], v[126:129], v[142:145], v[14:17]
	v_cvt_pk_bf16_f32 v7, v8, v9
	s_waitcnt lgkmcnt(1)
	v_mfma_f32_16x16x32_bf16 v[18:21], v[122:125], v[146:149], v[18:21]
	v_mfma_f32_16x16x32_bf16 v[22:25], v[126:129], v[146:149], v[22:25]
	s_waitcnt lgkmcnt(0)
	v_mfma_f32_16x16x32_bf16 v[26:29], v[122:125], v[150:153], v[26:29]
	v_mfma_f32_16x16x32_bf16 v[30:33], v[126:129], v[150:153], v[30:33]
	ds_read_b64_tr_b16 v[138:139], v111 offset:27328
	ds_read_b64_tr_b16 v[136:137], v111 offset:26240
	ds_read_b64_tr_b16 v[142:143], v111 offset:26272
	ds_read_b64_tr_b16 v[146:147], v111 offset:26304
	ds_read_b64_tr_b16 v[150:151], v111 offset:26336
	ds_read_b64_tr_b16 v[144:145], v111 offset:27360
	ds_read_b64_tr_b16 v[148:149], v111 offset:27392
	ds_read_b64_tr_b16 v[152:153], v111 offset:27424
	s_waitcnt lgkmcnt(6)
	v_mfma_f32_16x16x32_bf16 v[34:37], v[122:125], v[136:139], v[34:37]
	s_waitcnt lgkmcnt(2)
	v_mfma_f32_16x16x32_bf16 v[42:45], v[122:125], v[142:145], v[42:45]
	s_waitcnt lgkmcnt(1)
	v_mfma_f32_16x16x32_bf16 v[50:53], v[122:125], v[146:149], v[50:53]
	s_waitcnt lgkmcnt(0)
	v_mfma_f32_16x16x32_bf16 v[58:61], v[122:125], v[150:153], v[58:61]
	v_lshl_add_u64 v[122:123], s[4:5], 0, v[70:71]
	v_lshl_add_u64 v[4:5], v[122:123], 0, v[72:73]
	global_store_dwordx2 v[4:5], v[2:3], off sc1
	v_cvt_pk_bf16_f32 v2, v10, v11
	v_cvt_pk_bf16_f32 v3, v12, v13
	v_lshl_add_u64 v[10:11], v[122:123], 0, v[74:75]
	global_store_dwordx2 v[10:11], v[2:3], off sc1
	v_cvt_pk_bf16_f32 v2, v18, v19
	v_cvt_pk_bf16_f32 v3, v20, v21
	v_lshl_add_u64 v[10:11], v[122:123], 0, v[76:77]
	global_store_dwordx2 v[10:11], v[2:3], off sc1
	v_cvt_pk_bf16_f32 v2, v26, v27
	v_cvt_pk_bf16_f32 v3, v28, v29
	v_lshl_add_u64 v[10:11], v[122:123], 0, v[66:67]
	global_store_dwordx2 v[10:11], v[2:3], off sc1
	v_cvt_pk_bf16_f32 v2, v34, v35
	v_cvt_pk_bf16_f32 v3, v36, v37
	v_lshl_add_u64 v[10:11], v[122:123], 0, v[78:79]
	global_store_dwordx2 v[10:11], v[2:3], off sc1
	v_cvt_pk_bf16_f32 v2, v42, v43
	v_cvt_pk_bf16_f32 v3, v44, v45
	v_lshl_add_u64 v[10:11], v[122:123], 0, v[80:81]
	global_store_dwordx2 v[10:11], v[2:3], off sc1
	v_cvt_pk_bf16_f32 v2, v50, v51
	v_cvt_pk_bf16_f32 v3, v52, v53
	v_lshl_add_u64 v[10:11], v[122:123], 0, v[82:83]
	global_store_dwordx2 v[10:11], v[2:3], off sc1
	v_cvt_pk_bf16_f32 v2, v58, v59
	v_cvt_pk_bf16_f32 v3, v60, v61
	v_lshl_add_u64 v[10:11], v[122:123], 0, v[84:85]
	v_mfma_f32_16x16x32_bf16 v[38:41], v[126:129], v[136:139], v[38:41]
	global_store_dwordx2 v[10:11], v[2:3], off sc1
	v_lshl_add_u64 v[2:3], v[122:123], 0, 32
	global_store_dwordx2 v[4:5], v[6:7], off offset:32 sc1
	v_mfma_f32_16x16x32_bf16 v[46:49], v[126:129], v[142:145], v[46:49]
	v_cvt_pk_bf16_f32 v4, v14, v15
	v_cvt_pk_bf16_f32 v5, v16, v17
	v_lshl_add_u64 v[6:7], v[2:3], 0, v[74:75]
	v_mfma_f32_16x16x32_bf16 v[54:57], v[126:129], v[146:149], v[54:57]
	global_store_dwordx2 v[6:7], v[4:5], off sc1
	v_cvt_pk_bf16_f32 v4, v22, v23
	v_cvt_pk_bf16_f32 v5, v24, v25
	v_lshl_add_u64 v[6:7], v[2:3], 0, v[76:77]
	v_mfma_f32_16x16x32_bf16 v[62:65], v[126:129], v[150:153], v[62:65]
	global_store_dwordx2 v[6:7], v[4:5], off sc1
	v_cvt_pk_bf16_f32 v4, v30, v31
	v_cvt_pk_bf16_f32 v5, v32, v33
	v_lshl_add_u64 v[6:7], v[2:3], 0, v[66:67]
	global_store_dwordx2 v[6:7], v[4:5], off sc1
	v_cvt_pk_bf16_f32 v4, v38, v39
	v_cvt_pk_bf16_f32 v5, v40, v41
	v_lshl_add_u64 v[6:7], v[2:3], 0, v[78:79]
	global_store_dwordx2 v[6:7], v[4:5], off sc1
	v_cvt_pk_bf16_f32 v4, v46, v47
	v_cvt_pk_bf16_f32 v5, v48, v49
	v_lshl_add_u64 v[6:7], v[2:3], 0, v[80:81]
	global_store_dwordx2 v[6:7], v[4:5], off sc1
	v_cvt_pk_bf16_f32 v4, v54, v55
	v_cvt_pk_bf16_f32 v5, v56, v57
	v_lshl_add_u64 v[6:7], v[2:3], 0, v[82:83]
	global_store_dwordx2 v[6:7], v[4:5], off sc1
	v_cvt_pk_bf16_f32 v4, v62, v63
	v_cvt_pk_bf16_f32 v5, v64, v65
	v_lshl_add_u64 v[2:3], v[2:3], 0, v[84:85]
	global_store_dwordx2 v[2:3], v[4:5], off sc1
	s_waitcnt vmcnt(0)
	s_barrier
	s_and_saveexec_b64 s[4:5], s[34:35]
	s_cbranch_execz .LBB0_274
	s_mov_b64 s[22:23], exec
	v_mbcnt_lo_u32_b32 v2, s22, 0
	v_mbcnt_hi_u32_b32 v2, s23, v2
	v_cmp_eq_u32_e32 vcc, 0, v2
	s_and_b64 s[30:31], exec, vcc
	s_mov_b64 exec, s[30:31]
	s_cbranch_execz .LBB0_274
	s_lshl_b32 s8, s72, 3
	s_and_b32 s72, s8, 0x7fffffc0
	s_lshl_b64 s[30:31], s[72:73], 2
	s_add_u32 s30, s82, s30
	s_addc_u32 s31, s83, s31
	s_bcnt1_i32_b64 s8, s[22:23]
	v_mov_b32_e32 v2, s8
	global_atomic_add v67, v2, s[30:31]
	s_branch .LBB0_274

.LBB0_372:
	s_barrier
	s_waitcnt vmcnt(3)
	ds_write_b128 v136, v[98:101]
	s_waitcnt vmcnt(2)
	ds_write_b128 v136, v[102:105] offset:17408
	s_waitcnt vmcnt(1)
	ds_write_b128 v134, v[106:109]
	s_waitcnt vmcnt(0)
	ds_write_b128 v134, v[110:113] offset:17408
	v_add_u32_e32 v98, s19, v160
	v_add_u32_e32 v106, s19, v159
	v_mad_i64_i32 v[102:103], s[0:1], v98, s5, v[138:139]
	v_mad_i64_i32 v[110:111], s[0:1], v106, s5, v[138:139]
	s_waitcnt lgkmcnt(0)
	s_barrier
	global_load_dwordx4 v[98:101], v[102:103], off offset:1024
	s_nop 0
	global_load_dwordx4 v[102:105], v[102:103], off offset:2048
	s_nop 0
	global_load_dwordx4 v[106:109], v[110:111], off offset:1024
	s_nop 0
	global_load_dwordx4 v[110:113], v[110:111], off offset:2048
	ds_read_b128 v[114:117], v157
	ds_read_b128 v[118:121], v157 offset:64
	ds_read_b128 v[122:125], v157 offset:128
	ds_read_b128 v[126:129], v157 offset:192
	v_add_u32_e32 v162, s19, v158
	v_add_co_u32_e32 v130, vcc, 1, v162
	v_cvt_f32_i32_e32 v165, v162
	s_waitcnt lgkmcnt(3)
	v_mfma_f32_16x16x32_bf16 v[130:133], v[114:117], v[34:37], 0
	v_cvt_f32_i32_e32 v164, v161
	v_add_u32_e32 v163, -16, v162
	v_mul_f32_e32 v165, v142, v165
	v_mfma_f32_16x16x32_bf16 v[114:117], v[114:117], v[26:29], 0
	v_mul_f32_e32 v164, v144, v164
	v_exp_f32_e32 v165, v165
	v_exp_f32_e32 v164, v164
	s_waitcnt lgkmcnt(2)
	v_mfma_f32_16x16x32_bf16 v[130:133], v[118:121], v[30:33], v[130:133]
	v_cmp_gt_i32_e64 s[8:9], 0, v161
	v_mul_f32_e32 v167, v154, v165
	v_cmp_lt_i32_e64 s[6:7], 0, v161
	v_mfma_f32_16x16x32_bf16 v[114:117], v[118:121], v[22:25], v[114:117]
	v_add_u32_e32 v118, 16, v161
	v_cvt_f32_i32_e32 v119, v163
	v_cvt_f32_i32_e32 v118, v118
	s_waitcnt lgkmcnt(1)
	v_mfma_f32_16x16x32_bf16 v[114:117], v[122:125], v[6:9], v[114:117]
	v_mul_f32_e32 v166, v153, v164
	v_mul_f32_e32 v119, v142, v119
	v_cndmask_b32_e64 v167, 2.0, v167, s[8:9]
	v_mul_f32_e32 v168, v152, v165
	v_mul_f32_e32 v118, v144, v118
	v_exp_f32_e32 v119, v119
	v_cndmask_b32_e64 v166, v167, v166, s[6:7]
	v_cmp_lt_i32_e64 s[6:7], 1, v161
	v_mul_f32_e32 v167, v151, v164
	v_cndmask_b32_e64 v168, v168, 2.0, vcc
	v_exp_f32_e32 v118, v118
	v_cndmask_b32_e64 v167, v168, v167, s[6:7]
	v_mul_f32_e32 v169, v150, v165
	v_cmp_ne_u32_e64 s[6:7], -2, v162
	v_mfma_f32_16x16x32_bf16 v[130:133], v[122:125], v[14:17], v[130:133]
	v_cmp_lt_i32_e32 vcc, 2, v161
	v_mul_f32_e32 v168, v149, v164
	v_cndmask_b32_e64 v169, 2.0, v169, s[6:7]
	v_mul_f32_e32 v165, v146, v165
	v_cmp_ne_u32_e64 s[6:7], -3, v162
	s_waitcnt lgkmcnt(0)
	v_mfma_f32_16x16x32_bf16 v[114:117], v[126:129], v[2:5], v[114:117]
	v_cndmask_b32_e32 v168, v169, v168, vcc
	v_cmp_lt_i32_e32 vcc, 3, v161
	v_mul_f32_e32 v164, v148, v164
	v_cndmask_b32_e64 v165, 2.0, v165, s[6:7]
	v_mul_f32_e32 v121, v154, v119
	v_cmp_ne_u32_e64 s[6:7], 0, v163
	v_cndmask_b32_e32 v164, v165, v164, vcc
	v_cmp_lt_i32_e32 vcc, -16, v161
	v_mul_f32_e32 v120, v153, v118
	v_cndmask_b32_e64 v121, 2.0, v121, s[6:7]
	v_cndmask_b32_e32 v120, v121, v120, vcc
	v_mul_f32_e32 v121, v152, v119
	v_cmp_ne_u32_e64 s[6:7], 15, v162
	v_mfma_f32_16x16x32_bf16 v[130:133], v[126:129], v[10:13], v[130:133]
	v_mul_f32_e32 v114, v120, v114
	v_cmp_lt_i32_e32 vcc, -15, v161
	v_mul_f32_e32 v120, v151, v118
	v_cndmask_b32_e64 v121, 2.0, v121, s[6:7]
	v_cndmask_b32_e32 v120, v121, v120, vcc
	v_mul_f32_e32 v121, v150, v119
	v_cmp_ne_u32_e64 s[6:7], 14, v162
	v_mul_f32_e32 v115, v120, v115
	v_cmp_lt_i32_e32 vcc, -14, v161
	v_mul_f32_e32 v120, v149, v118
	v_cndmask_b32_e64 v121, 2.0, v121, s[6:7]
	v_mul_f32_e32 v119, v146, v119
	v_cmp_ne_u32_e64 s[6:7], 13, v162
	v_cndmask_b32_e32 v120, v121, v120, vcc
	v_cmp_lt_i32_e32 vcc, -13, v161
	v_mul_f32_e32 v118, v148, v118
	v_cndmask_b32_e64 v119, 2.0, v119, s[6:7]
	v_mul_f32_e32 v130, v166, v130
	v_mul_f32_e32 v131, v167, v131
	v_cndmask_b32_e32 v118, v119, v118, vcc
	v_mul_f32_e32 v132, v168, v132
	v_mul_f32_e32 v133, v164, v133
	v_cvt_pk_bf16_f32 v130, v130, v131
	v_cvt_pk_bf16_f32 v131, v132, v133
	ds_write_b64 v156, v[130:131] offset:53248
	v_mul_f32_e32 v116, v120, v116
	v_mul_f32_e32 v117, v118, v117
	v_cvt_pk_bf16_f32 v114, v114, v115
	v_cvt_pk_bf16_f32 v115, v116, v117
	ds_write_b64 v156, v[114:115] offset:55552
	ds_read_b128 v[114:117], v157 offset:4352
	ds_read_b128 v[118:121], v157 offset:4416
	ds_read_b128 v[122:125], v157 offset:4480
	ds_read_b128 v[126:129], v157 offset:4544
	s_waitcnt lgkmcnt(3)
	v_mfma_f32_16x16x32_bf16 v[130:133], v[114:117], v[34:37], 0
	v_add_u32_e32 v171, 16, v162
	v_add_u32_e32 v163, -16, v161
	v_cvt_f32_i32_e32 v169, v171
	s_waitcnt lgkmcnt(2)
	v_mfma_f32_16x16x32_bf16 v[130:133], v[118:121], v[30:33], v[130:133]
	v_cvt_f32_i32_e32 v165, v163
	v_cmp_gt_i32_e64 s[6:7], 0, v163
	v_mul_f32_e32 v169, v142, v169
	v_mfma_f32_16x16x32_bf16 v[114:117], v[114:117], v[26:29], 0
	v_mul_f32_e32 v165, v144, v165
	v_exp_f32_e32 v169, v169
	v_exp_f32_e32 v165, v165
	s_waitcnt lgkmcnt(1)
	v_mfma_f32_16x16x32_bf16 v[130:133], v[122:125], v[14:17], v[130:133]
	v_cmp_lt_i32_e32 vcc, 0, v163
	v_mul_f32_e32 v174, v154, v169
	v_mul_f32_e32 v173, v153, v165
	v_mfma_f32_16x16x32_bf16 v[114:117], v[118:121], v[22:25], v[114:117]
	v_cndmask_b32_e64 v170, 2.0, v174, s[6:7]
	v_cndmask_b32_e32 v170, v170, v173, vcc
	v_cmp_ne_u32_e64 s[6:7], s18, v162
	s_waitcnt lgkmcnt(0)
	v_mfma_f32_16x16x32_bf16 v[130:133], v[126:129], v[10:13], v[130:133]
	v_cmp_lt_i32_e32 vcc, 1, v163
	v_mul_f32_e32 v175, v151, v165
	v_mul_f32_e32 v177, v149, v165
	v_mfma_f32_16x16x32_bf16 v[114:117], v[122:125], v[6:9], v[114:117]
	v_mul_f32_e32 v179, v148, v165
	s_nop 2
	v_mul_f32_e32 v130, v170, v130
	v_mul_f32_e32 v170, v152, v169
	v_cndmask_b32_e64 v176, 2.0, v170, s[6:7]
	v_cndmask_b32_e32 v170, v176, v175, vcc
	v_mul_f32_e32 v131, v170, v131
	v_mul_f32_e32 v170, v150, v169
	v_cmp_ne_u32_e64 s[6:7], s21, v162
	v_mfma_f32_16x16x32_bf16 v[114:117], v[126:129], v[2:5], v[114:117]
	v_cmp_lt_i32_e32 vcc, 2, v163
	v_cndmask_b32_e64 v178, 2.0, v170, s[6:7]
	v_cmp_ne_u32_e64 s[6:7], s22, v162
	v_cndmask_b32_e32 v170, v178, v177, vcc
	v_cmp_lt_i32_e32 vcc, 3, v163
	v_mul_f32_e32 v163, v146, v169
	v_cndmask_b32_e64 v180, 2.0, v163, s[6:7]
	v_cndmask_b32_e32 v163, v180, v179, vcc
	v_mul_f32_e32 v114, v166, v114
	v_mul_f32_e32 v115, v167, v115
	v_mul_f32_e32 v132, v170, v132
	v_mul_f32_e32 v133, v163, v133
	v_cvt_pk_bf16_f32 v130, v130, v131
	v_cvt_pk_bf16_f32 v131, v132, v133
	ds_write_b64 v156, v[130:131] offset:53280
	v_mul_f32_e32 v116, v168, v116
	v_mul_f32_e32 v117, v164, v117
	v_cvt_pk_bf16_f32 v114, v114, v115
	v_cvt_pk_bf16_f32 v115, v116, v117
	ds_write_b64 v156, v[114:115] offset:55584
	ds_read_b128 v[114:117], v157 offset:8704
	ds_read_b128 v[118:121], v157 offset:8768
	ds_read_b128 v[122:125], v157 offset:8832
	ds_read_b128 v[126:129], v157 offset:8896
	s_waitcnt lgkmcnt(3)
	v_mfma_f32_16x16x32_bf16 v[130:133], v[114:117], v[34:37], 0
	v_add_u32_e32 v172, 32, v162
	v_subrev_u32_e32 v181, 32, v161
	v_cvt_f32_i32_e32 v164, v172
	s_waitcnt lgkmcnt(2)
	v_mfma_f32_16x16x32_bf16 v[130:133], v[118:121], v[30:33], v[130:133]
	v_cvt_f32_i32_e32 v163, v181
	v_cmp_gt_i32_e64 s[6:7], 0, v181
	v_mul_f32_e32 v164, v142, v164
	v_mfma_f32_16x16x32_bf16 v[114:117], v[114:117], v[26:29], 0
	v_mul_f32_e32 v163, v144, v163
	v_exp_f32_e32 v164, v164
	v_exp_f32_e32 v163, v163
	s_waitcnt lgkmcnt(1)
	v_mfma_f32_16x16x32_bf16 v[130:133], v[122:125], v[14:17], v[130:133]
	v_cmp_lt_i32_e32 vcc, 0, v181
	v_mul_f32_e32 v170, v154, v164
	v_mul_f32_e32 v169, v153, v163
	v_mfma_f32_16x16x32_bf16 v[114:117], v[118:121], v[22:25], v[114:117]
	v_cndmask_b32_e64 v165, 2.0, v170, s[6:7]
	v_cndmask_b32_e32 v165, v165, v169, vcc
	v_cmp_ne_u32_e64 s[6:7], s23, v162
	s_waitcnt lgkmcnt(0)
	v_mfma_f32_16x16x32_bf16 v[130:133], v[126:129], v[10:13], v[130:133]
	v_cmp_lt_i32_e32 vcc, 1, v181
	v_mul_f32_e32 v167, v151, v163
	v_mul_f32_e32 v166, v150, v164
	v_mfma_f32_16x16x32_bf16 v[114:117], v[122:125], v[6:9], v[114:117]
	s_add_i32 s19, s19, 64
	s_nop 2
	v_mul_f32_e32 v130, v165, v130
	v_mul_f32_e32 v165, v152, v164
	v_cndmask_b32_e64 v168, 2.0, v165, s[6:7]
	v_cndmask_b32_e32 v165, v168, v167, vcc
	v_cmp_ne_u32_e64 s[6:7], s24, v162
	v_mul_f32_e32 v131, v165, v131
	v_cmp_lt_i32_e32 vcc, 2, v181
	v_mul_f32_e32 v165, v149, v163
	v_cndmask_b32_e64 v166, 2.0, v166, s[6:7]
	v_mul_f32_e32 v164, v146, v164
	v_cmp_ne_u32_e64 s[6:7], s25, v162
	v_mfma_f32_16x16x32_bf16 v[114:117], v[126:129], v[2:5], v[114:117]
	v_cndmask_b32_e32 v182, v166, v165, vcc
	v_cmp_lt_i32_e32 vcc, 3, v181
	v_mul_f32_e32 v163, v148, v163
	v_cndmask_b32_e64 v164, 2.0, v164, s[6:7]
	v_cmp_ne_u32_e64 s[6:7], 0, v171
	v_mul_f32_e32 v132, v182, v132
	v_cndmask_b32_e32 v182, v164, v163, vcc
	v_cmp_lt_i32_e32 vcc, -16, v181
	v_cndmask_b32_e64 v118, 2.0, v174, s[6:7]
	v_mul_f32_e32 v133, v182, v133
	v_cndmask_b32_e32 v118, v118, v173, vcc
	v_cmp_lt_i32_e32 vcc, -15, v181
	v_mul_f32_e32 v114, v118, v114
	v_cvt_pk_bf16_f32 v130, v130, v131
	v_cvt_pk_bf16_f32 v131, v132, v133
	ds_write_b64 v156, v[130:131] offset:53312
	v_cndmask_b32_e32 v118, v176, v175, vcc
	v_cmp_lt_i32_e32 vcc, -14, v181
	v_mul_f32_e32 v115, v118, v115
	v_cvt_pk_bf16_f32 v114, v114, v115
	v_add_u32_e32 v174, 48, v162
	v_cndmask_b32_e32 v118, v178, v177, vcc
	v_cmp_lt_i32_e32 vcc, -13, v181
	v_mul_f32_e32 v116, v118, v116
	v_subrev_u32_e32 v171, 48, v161
	v_cndmask_b32_e32 v118, v180, v179, vcc
	v_mul_f32_e32 v117, v118, v117
	v_cvt_pk_bf16_f32 v115, v116, v117
	ds_write_b64 v156, v[114:115] offset:55616
	ds_read_b128 v[114:117], v157 offset:13056
	ds_read_b128 v[118:121], v157 offset:13120
	ds_read_b128 v[122:125], v157 offset:13184
	ds_read_b128 v[126:129], v157 offset:13248
	s_waitcnt lgkmcnt(3)
	v_mfma_f32_16x16x32_bf16 v[130:133], v[114:117], v[34:37], 0
	v_cvt_f32_i32_e32 v174, v174
	v_cvt_f32_i32_e32 v173, v171
	v_cmp_gt_i32_e64 s[6:7], 0, v171
	s_waitcnt lgkmcnt(2)
	v_mfma_f32_16x16x32_bf16 v[130:133], v[118:121], v[30:33], v[130:133]
	v_mul_f32_e32 v174, v142, v174
	v_mul_f32_e32 v173, v144, v173
	v_exp_f32_e32 v174, v174
	v_mfma_f32_16x16x32_bf16 v[114:117], v[114:117], v[26:29], 0
	v_exp_f32_e32 v173, v173
	v_cmp_lt_i32_e32 vcc, 0, v171
	v_mul_f32_e32 v176, v154, v174
	s_waitcnt lgkmcnt(1)
	v_mfma_f32_16x16x32_bf16 v[130:133], v[122:125], v[14:17], v[130:133]
	v_mul_f32_e32 v175, v153, v173
	v_cndmask_b32_e64 v176, 2.0, v176, s[6:7]
	v_cndmask_b32_e32 v175, v176, v175, vcc
	v_mfma_f32_16x16x32_bf16 v[114:117], v[118:121], v[22:25], v[114:117]
	v_mul_f32_e32 v176, v152, v174
	v_cmp_ne_u32_e64 s[6:7], s26, v162
	v_cmp_lt_i32_e32 vcc, 1, v171
	s_waitcnt lgkmcnt(0)
	v_mfma_f32_16x16x32_bf16 v[130:133], v[126:129], v[10:13], v[130:133]
	v_cndmask_b32_e64 v176, 2.0, v176, s[6:7]
	v_cmp_ne_u32_e64 s[6:7], s27, v162
	v_subrev_u32_e32 v161, 64, v161
	v_mfma_f32_16x16x32_bf16 v[114:117], v[122:125], v[6:9], v[114:117]
	s_cmpk_eq_i32 s19, 0xc0
	s_nop 2
	v_mul_f32_e32 v130, v175, v130
	v_mul_f32_e32 v175, v151, v173
	v_cndmask_b32_e32 v175, v176, v175, vcc
	v_mul_f32_e32 v176, v150, v174
	v_mul_f32_e32 v131, v175, v131
	v_cmp_lt_i32_e32 vcc, 2, v171
	v_mul_f32_e32 v175, v149, v173
	v_cndmask_b32_e64 v176, 2.0, v176, s[6:7]
	v_mul_f32_e32 v174, v146, v174
	v_cmp_ne_u32_e64 s[6:7], s28, v162
	v_mfma_f32_16x16x32_bf16 v[114:117], v[126:129], v[2:5], v[114:117]
	v_cndmask_b32_e32 v175, v176, v175, vcc
	v_cmp_lt_i32_e32 vcc, 3, v171
	v_mul_f32_e32 v173, v148, v173
	v_cndmask_b32_e64 v162, 2.0, v174, s[6:7]
	v_cmp_ne_u32_e64 s[6:7], 0, v172
	v_cndmask_b32_e32 v162, v162, v173, vcc
	v_cmp_lt_i32_e32 vcc, -16, v171
	v_cndmask_b32_e64 v118, 2.0, v170, s[6:7]
	v_mul_f32_e32 v132, v175, v132
	v_cndmask_b32_e32 v118, v118, v169, vcc
	v_cmp_lt_i32_e32 vcc, -15, v171
	v_mul_f32_e32 v114, v118, v114
	v_mul_f32_e32 v133, v162, v133
	v_cndmask_b32_e32 v118, v168, v167, vcc
	v_cmp_lt_i32_e32 vcc, -14, v171
	v_mul_f32_e32 v115, v118, v115
	v_cvt_pk_bf16_f32 v130, v130, v131
	v_cvt_pk_bf16_f32 v131, v132, v133
	ds_write_b64 v156, v[130:131] offset:53344
	v_cndmask_b32_e32 v118, v166, v165, vcc
	v_cmp_lt_i32_e32 vcc, -13, v171
	v_mul_f32_e32 v116, v118, v116
	v_cvt_pk_bf16_f32 v114, v114, v115
	s_nop 0
	v_cndmask_b32_e32 v118, v164, v163, vcc
	v_mul_f32_e32 v117, v118, v117
	v_cvt_pk_bf16_f32 v115, v116, v117
	ds_write_b64 v156, v[114:115] offset:55648
	s_waitcnt lgkmcnt(0)
	ds_read_b128 v[126:129], v147 offset:53248
	ds_read_b128 v[114:117], v147 offset:53312
	ds_read_b128 v[122:125], v147 offset:55552
	ds_read_b128 v[118:121], v147 offset:55616
	ds_read_b64_tr_b16 v[132:133], v137 offset:18496
	ds_read_b64_tr_b16 v[130:131], v137 offset:17408
	ds_read_b64_tr_b16 v[162:163], v137 offset:17440
	s_waitcnt lgkmcnt(1)
	v_mfma_f32_16x16x32_bf16 v[94:97], v[126:129], v[130:133], v[94:97]
	v_mfma_f32_16x16x32_bf16 v[82:85], v[122:125], v[130:133], v[82:85]
	ds_read_b64_tr_b16 v[130:131], v137 offset:26112
	ds_read_b64_tr_b16 v[132:133], v137 offset:27200
	ds_read_b64_tr_b16 v[164:165], v137 offset:18528
	s_waitcnt lgkmcnt(1)
	v_mfma_f32_16x16x32_bf16 v[94:97], v[114:117], v[130:133], v[94:97]
	v_mfma_f32_16x16x32_bf16 v[82:85], v[118:121], v[130:133], v[82:85]
	ds_read_b64_tr_b16 v[130:131], v137 offset:26144
	ds_read_b64_tr_b16 v[132:133], v137 offset:27232
	s_waitcnt lgkmcnt(2)
	v_mfma_f32_16x16x32_bf16 v[90:93], v[126:129], v[162:165], v[90:93]
	v_mfma_f32_16x16x32_bf16 v[70:73], v[122:125], v[162:165], v[70:73]
	s_waitcnt lgkmcnt(0)
	v_mfma_f32_16x16x32_bf16 v[90:93], v[114:117], v[130:133], v[90:93]
	v_mfma_f32_16x16x32_bf16 v[70:73], v[118:121], v[130:133], v[70:73]
	ds_read_b64_tr_b16 v[130:131], v137 offset:17472
	ds_read_b64_tr_b16 v[132:133], v137 offset:18560
	s_waitcnt lgkmcnt(0)
	v_mfma_f32_16x16x32_bf16 v[86:89], v[126:129], v[130:133], v[86:89]
	v_mfma_f32_16x16x32_bf16 v[66:69], v[122:125], v[130:133], v[66:69]
	ds_read_b64_tr_b16 v[130:131], v137 offset:26176
	ds_read_b64_tr_b16 v[132:133], v137 offset:27264
	s_waitcnt lgkmcnt(0)
	v_mfma_f32_16x16x32_bf16 v[86:89], v[114:117], v[130:133], v[86:89]
	v_mfma_f32_16x16x32_bf16 v[66:69], v[118:121], v[130:133], v[66:69]
	ds_read_b64_tr_b16 v[130:131], v137 offset:17504
	ds_read_b64_tr_b16 v[132:133], v137 offset:18592
	s_waitcnt lgkmcnt(0)
	v_mfma_f32_16x16x32_bf16 v[78:81], v[126:129], v[130:133], v[78:81]
	v_mfma_f32_16x16x32_bf16 v[62:65], v[122:125], v[130:133], v[62:65]
	ds_read_b64_tr_b16 v[130:131], v137 offset:26208
	ds_read_b64_tr_b16 v[132:133], v137 offset:27296
	s_waitcnt lgkmcnt(0)
	v_mfma_f32_16x16x32_bf16 v[78:81], v[114:117], v[130:133], v[78:81]
	v_mfma_f32_16x16x32_bf16 v[62:65], v[118:121], v[130:133], v[62:65]
	ds_read_b64_tr_b16 v[130:131], v137 offset:17536
	ds_read_b64_tr_b16 v[132:133], v137 offset:18624
	s_waitcnt lgkmcnt(0)
	v_mfma_f32_16x16x32_bf16 v[58:61], v[126:129], v[130:133], v[58:61]
	v_mfma_f32_16x16x32_bf16 v[46:49], v[122:125], v[130:133], v[46:49]
	ds_read_b64_tr_b16 v[130:131], v137 offset:26240
	ds_read_b64_tr_b16 v[132:133], v137 offset:27328
	s_waitcnt lgkmcnt(0)
	v_mfma_f32_16x16x32_bf16 v[58:61], v[114:117], v[130:133], v[58:61]
	v_mfma_f32_16x16x32_bf16 v[46:49], v[118:121], v[130:133], v[46:49]
	ds_read_b64_tr_b16 v[130:131], v137 offset:17568
	ds_read_b64_tr_b16 v[132:133], v137 offset:18656
	s_waitcnt lgkmcnt(0)
	v_mfma_f32_16x16x32_bf16 v[54:57], v[126:129], v[130:133], v[54:57]
	v_mfma_f32_16x16x32_bf16 v[42:45], v[122:125], v[130:133], v[42:45]
	ds_read_b64_tr_b16 v[130:131], v137 offset:26272
	ds_read_b64_tr_b16 v[132:133], v137 offset:27360
	s_waitcnt lgkmcnt(0)
	v_mfma_f32_16x16x32_bf16 v[54:57], v[114:117], v[130:133], v[54:57]
	v_mfma_f32_16x16x32_bf16 v[42:45], v[118:121], v[130:133], v[42:45]
	ds_read_b64_tr_b16 v[130:131], v137 offset:17600
	ds_read_b64_tr_b16 v[132:133], v137 offset:18688
	s_waitcnt lgkmcnt(0)
	v_mfma_f32_16x16x32_bf16 v[50:53], v[126:129], v[130:133], v[50:53]
	v_mfma_f32_16x16x32_bf16 v[38:41], v[122:125], v[130:133], v[38:41]
	ds_read_b64_tr_b16 v[130:131], v137 offset:26304
	ds_read_b64_tr_b16 v[132:133], v137 offset:27392
	s_waitcnt lgkmcnt(0)
	v_mfma_f32_16x16x32_bf16 v[50:53], v[114:117], v[130:133], v[50:53]
	v_mfma_f32_16x16x32_bf16 v[38:41], v[118:121], v[130:133], v[38:41]
	ds_read_b64_tr_b16 v[130:131], v137 offset:17632
	ds_read_b64_tr_b16 v[132:133], v137 offset:18720
	s_waitcnt lgkmcnt(0)
	v_mfma_f32_16x16x32_bf16 v[18:21], v[122:125], v[130:133], v[18:21]
	ds_read_b64_tr_b16 v[122:123], v137 offset:26336
	ds_read_b64_tr_b16 v[124:125], v137 offset:27424
	v_mfma_f32_16x16x32_bf16 v[74:77], v[126:129], v[130:133], v[74:77]
	s_waitcnt lgkmcnt(0)
	v_mfma_f32_16x16x32_bf16 v[74:77], v[114:117], v[122:125], v[74:77]
	v_mfma_f32_16x16x32_bf16 v[18:21], v[118:121], v[122:125], v[18:21]
	s_cbranch_scc0 .LBB0_372
	s_barrier
	s_waitcnt vmcnt(3)
	ds_write_b128 v136, v[98:101]
	s_waitcnt vmcnt(2)
	ds_write_b128 v136, v[102:105] offset:17408
	s_waitcnt vmcnt(1)
	ds_write_b128 v134, v[106:109]
	s_waitcnt vmcnt(0)
	ds_write_b128 v134, v[110:113] offset:17408
	s_waitcnt lgkmcnt(0)
	s_barrier
	ds_read_b128 v[98:101], v157
	ds_read_b128 v[102:105], v157 offset:64
	v_sub_u32_e32 v119, 0xc0, v155
	v_add_u32_e32 v118, 0xffffff40, v155
	v_cvt_f32_i32_e32 v119, v119
	v_cvt_f32_i32_e32 v118, v118
	s_waitcnt lgkmcnt(1)
	v_mfma_f32_16x16x32_bf16 v[106:109], v[98:101], v[34:37], 0
	ds_read_b128 v[110:113], v157 offset:128
	ds_read_b128 v[114:117], v157 offset:192
	v_mul_f32_e32 v119, v142, v119
	v_mul_f32_e32 v118, v144, v118
	v_mfma_f32_16x16x32_bf16 v[98:101], v[98:101], v[26:29], 0
	v_exp_f32_e32 v119, v119
	v_exp_f32_e32 v118, v118
	s_movk_i32 s0, 0xc0
	s_waitcnt lgkmcnt(2)
	v_mfma_f32_16x16x32_bf16 v[106:109], v[102:105], v[30:33], v[106:109]
	v_mul_f32_e32 v121, v119, v154
	v_cmp_ne_u32_e32 vcc, s0, v155
	v_mul_f32_e32 v120, v118, v153
	v_mfma_f32_16x16x32_bf16 v[98:101], v[102:105], v[22:25], v[98:101]
	v_sub_u32_e32 v103, 0xb0, v155
	v_add_u32_e32 v102, 0xffffff50, v155
	v_cvt_f32_i32_e32 v103, v103
	v_cvt_f32_i32_e32 v102, v102
	v_cndmask_b32_e32 v121, 2.0, v121, vcc
	v_cmp_lt_i32_e32 vcc, s0, v155
	s_movk_i32 s0, 0xc1
	v_mul_f32_e32 v122, v152, v119
	v_cndmask_b32_e32 v120, v121, v120, vcc
	v_cmp_ne_u32_e32 vcc, s0, v155
	v_mul_f32_e32 v121, v151, v118
	s_waitcnt lgkmcnt(1)
	v_mfma_f32_16x16x32_bf16 v[98:101], v[110:113], v[6:9], v[98:101]
	v_cndmask_b32_e32 v122, 2.0, v122, vcc
	v_cmp_lt_i32_e32 vcc, s0, v155
	s_movk_i32 s0, 0xc2
	v_mul_f32_e32 v103, v142, v103
	v_cndmask_b32_e32 v121, v122, v121, vcc
	v_mul_f32_e32 v123, v119, v150
	v_cmp_ne_u32_e32 vcc, s0, v155
	v_mul_f32_e32 v102, v144, v102
	v_exp_f32_e32 v103, v103
	v_mul_f32_e32 v122, v118, v149
	v_cndmask_b32_e32 v123, 2.0, v123, vcc
	v_cmp_lt_i32_e32 vcc, s0, v155
	s_movk_i32 s0, 0xc3
	v_exp_f32_e32 v102, v102
	v_cndmask_b32_e32 v122, v123, v122, vcc
	v_mul_f32_e32 v119, v119, v146
	v_cmp_ne_u32_e32 vcc, s0, v155
	v_mul_f32_e32 v118, v118, v148
	s_waitcnt lgkmcnt(0)
	v_mfma_f32_16x16x32_bf16 v[98:101], v[114:117], v[2:5], v[98:101]
	v_cndmask_b32_e32 v119, 2.0, v119, vcc
	v_cmp_lt_i32_e32 vcc, s0, v155
	s_movk_i32 s0, 0xb0
	v_mfma_f32_16x16x32_bf16 v[106:109], v[110:113], v[14:17], v[106:109]
	v_cndmask_b32_e32 v118, v119, v118, vcc
	v_mul_f32_e32 v105, v103, v154
	v_cmp_ne_u32_e32 vcc, s0, v155
	v_mul_f32_e32 v104, v102, v153
	v_mfma_f32_16x16x32_bf16 v[106:109], v[114:117], v[10:13], v[106:109]
	v_cndmask_b32_e32 v105, 2.0, v105, vcc
	v_cmp_lt_i32_e32 vcc, s0, v155
	s_movk_i32 s0, 0xb1
	v_sub_u32_e32 v123, 0xd0, v155
	v_cndmask_b32_e32 v104, v105, v104, vcc
	v_mul_f32_e32 v105, v152, v103
	v_cmp_ne_u32_e32 vcc, s0, v155
	v_mul_f32_e32 v98, v104, v98
	v_mul_f32_e32 v104, v151, v102
	v_cndmask_b32_e32 v105, 2.0, v105, vcc
	v_cmp_lt_i32_e32 vcc, s0, v155
	s_movk_i32 s0, 0xb2
	v_mul_f32_e32 v106, v120, v106
	v_cndmask_b32_e32 v104, v105, v104, vcc
	v_mul_f32_e32 v105, v103, v150
	v_cmp_ne_u32_e32 vcc, s0, v155
	v_mul_f32_e32 v99, v104, v99
	v_mul_f32_e32 v104, v102, v149
	v_cndmask_b32_e32 v105, 2.0, v105, vcc
	v_cmp_lt_i32_e32 vcc, s0, v155
	s_movk_i32 s0, 0xb3
	v_mul_f32_e32 v103, v103, v146
	v_cndmask_b32_e32 v104, v105, v104, vcc
	v_cmp_ne_u32_e32 vcc, s0, v155
	v_mul_f32_e32 v102, v102, v148
	v_mul_f32_e32 v107, v121, v107
	v_cndmask_b32_e32 v103, 2.0, v103, vcc
	v_cmp_lt_i32_e32 vcc, s0, v155
	v_mul_f32_e32 v108, v122, v108
	v_mul_f32_e32 v109, v118, v109
	v_cndmask_b32_e32 v102, v103, v102, vcc
	v_cvt_pk_bf16_f32 v106, v106, v107
	v_cvt_pk_bf16_f32 v107, v108, v109
	ds_write_b64 v156, v[106:107] offset:53248
	v_mul_f32_e32 v100, v104, v100
	v_mul_f32_e32 v101, v102, v101
	v_cvt_pk_bf16_f32 v98, v98, v99
	v_cvt_pk_bf16_f32 v99, v100, v101
	ds_write_b64 v156, v[98:99] offset:55552
	ds_read_b128 v[98:101], v157 offset:4352
	ds_read_b128 v[102:105], v157 offset:4416
	v_add_u32_e32 v119, 0xffffff30, v155
	v_cvt_f32_i32_e32 v123, v123
	v_cvt_f32_i32_e32 v119, v119
	s_waitcnt lgkmcnt(1)
	v_mfma_f32_16x16x32_bf16 v[106:109], v[98:101], v[34:37], 0
	ds_read_b128 v[110:113], v157 offset:4480
	ds_read_b128 v[114:117], v157 offset:4544
	v_mul_f32_e32 v123, v142, v123
	v_mul_f32_e32 v119, v144, v119
	v_mfma_f32_16x16x32_bf16 v[98:101], v[98:101], v[26:29], 0
	v_exp_f32_e32 v123, v123
	v_exp_f32_e32 v119, v119
	s_movk_i32 s0, 0xd0
	s_waitcnt lgkmcnt(2)
	v_mfma_f32_16x16x32_bf16 v[106:109], v[102:105], v[30:33], v[106:109]
	v_mul_f32_e32 v125, v123, v154
	v_cmp_ne_u32_e32 vcc, s0, v155
	v_mul_f32_e32 v124, v119, v153
	v_mfma_f32_16x16x32_bf16 v[98:101], v[102:105], v[22:25], v[98:101]
	v_cndmask_b32_e32 v125, 2.0, v125, vcc
	v_cmp_lt_i32_e32 vcc, s0, v155
	s_movk_i32 s0, 0xd1
	s_waitcnt lgkmcnt(1)
	v_mfma_f32_16x16x32_bf16 v[106:109], v[110:113], v[14:17], v[106:109]
	v_cndmask_b32_e32 v124, v125, v124, vcc
	v_mul_f32_e32 v126, v152, v123
	v_cmp_ne_u32_e32 vcc, s0, v155
	v_mfma_f32_16x16x32_bf16 v[98:101], v[110:113], v[6:9], v[98:101]
	v_mul_f32_e32 v125, v151, v119
	v_cndmask_b32_e32 v126, 2.0, v126, vcc
	v_cmp_lt_i32_e32 vcc, s0, v155
	s_movk_i32 s0, 0xd2
	v_mul_f32_e32 v127, v123, v150
	v_cndmask_b32_e32 v125, v126, v125, vcc
	v_cmp_ne_u32_e32 vcc, s0, v155
	s_waitcnt lgkmcnt(0)
	v_mfma_f32_16x16x32_bf16 v[106:109], v[114:117], v[10:13], v[106:109]
	v_mul_f32_e32 v126, v119, v149
	v_cndmask_b32_e32 v127, 2.0, v127, vcc
	v_cmp_lt_i32_e32 vcc, s0, v155
	s_movk_i32 s0, 0xd3
	v_mfma_f32_16x16x32_bf16 v[98:101], v[114:117], v[2:5], v[98:101]
	v_cndmask_b32_e32 v126, v127, v126, vcc
	v_mul_f32_e32 v123, v123, v146
	v_cmp_ne_u32_e32 vcc, s0, v155
	v_mul_f32_e32 v119, v119, v148
	v_mul_f32_e32 v106, v124, v106
	v_cndmask_b32_e32 v123, 2.0, v123, vcc
	v_cmp_lt_i32_e32 vcc, s0, v155
	s_nop 0
	v_mul_f32_e32 v98, v120, v98
	v_mul_f32_e32 v99, v121, v99
	v_cndmask_b32_e32 v119, v123, v119, vcc
	v_mul_f32_e32 v103, v119, v109
	v_mul_f32_e32 v107, v125, v107
	v_mul_f32_e32 v108, v126, v108
	v_cvt_pk_bf16_f32 v102, v106, v107
	v_cvt_pk_bf16_f32 v103, v108, v103
	ds_write_b64 v156, v[102:103] offset:53280
	v_mul_f32_e32 v100, v122, v100
	v_mul_f32_e32 v101, v118, v101
	v_cvt_pk_bf16_f32 v98, v98, v99
	v_cvt_pk_bf16_f32 v99, v100, v101
	ds_write_b64 v156, v[98:99] offset:55584
	ds_read_b128 v[98:101], v157 offset:8704
	ds_read_b128 v[102:105], v157 offset:8768
	v_sub_u32_e32 v120, 0xe0, v155
	v_add_u32_e32 v118, 0xffffff20, v155
	v_cvt_f32_i32_e32 v120, v120
	v_cvt_f32_i32_e32 v118, v118
	s_waitcnt lgkmcnt(1)
	v_mfma_f32_16x16x32_bf16 v[106:109], v[98:101], v[34:37], 0
	ds_read_b128 v[110:113], v157 offset:8832
	ds_read_b128 v[114:117], v157 offset:8896
	v_mul_f32_e32 v120, v142, v120
	v_mul_f32_e32 v118, v144, v118
	v_mfma_f32_16x16x32_bf16 v[98:101], v[98:101], v[26:29], 0
	v_exp_f32_e32 v120, v120
	v_exp_f32_e32 v118, v118
	s_movk_i32 s0, 0xe0
	s_waitcnt lgkmcnt(2)
	v_mfma_f32_16x16x32_bf16 v[106:109], v[102:105], v[30:33], v[106:109]
	v_mul_f32_e32 v122, v120, v154
	v_cmp_ne_u32_e32 vcc, s0, v155
	v_mul_f32_e32 v121, v118, v153
	v_mfma_f32_16x16x32_bf16 v[98:101], v[102:105], v[22:25], v[98:101]
	v_cndmask_b32_e32 v122, 2.0, v122, vcc
	v_cmp_lt_i32_e32 vcc, s0, v155
	s_movk_i32 s0, 0xe1
	s_waitcnt lgkmcnt(1)
	v_mfma_f32_16x16x32_bf16 v[106:109], v[110:113], v[14:17], v[106:109]
	v_cndmask_b32_e32 v121, v122, v121, vcc
	v_mul_f32_e32 v123, v152, v120
	v_cmp_ne_u32_e32 vcc, s0, v155
	v_mfma_f32_16x16x32_bf16 v[98:101], v[110:113], v[6:9], v[98:101]
	v_mul_f32_e32 v122, v151, v118
	v_cndmask_b32_e32 v123, 2.0, v123, vcc
	v_cmp_lt_i32_e32 vcc, s0, v155
	s_movk_i32 s0, 0xe2
	v_mul_f32_e32 v127, v120, v150
	v_cndmask_b32_e32 v122, v123, v122, vcc
	v_cmp_ne_u32_e32 vcc, s0, v155
	s_waitcnt lgkmcnt(0)
	v_mfma_f32_16x16x32_bf16 v[106:109], v[114:117], v[10:13], v[106:109]
	v_mul_f32_e32 v123, v118, v149
	v_cndmask_b32_e32 v127, 2.0, v127, vcc
	v_cmp_lt_i32_e32 vcc, s0, v155
	s_movk_i32 s0, 0xe3
	v_mfma_f32_16x16x32_bf16 v[98:101], v[114:117], v[2:5], v[98:101]
	v_cndmask_b32_e32 v123, v127, v123, vcc
	v_mul_f32_e32 v120, v120, v146
	v_cmp_ne_u32_e32 vcc, s0, v155
	v_mul_f32_e32 v118, v118, v148
	v_mul_f32_e32 v106, v121, v106
	v_cndmask_b32_e32 v120, 2.0, v120, vcc
	v_cmp_lt_i32_e32 vcc, s0, v155
	s_nop 0
	v_mul_f32_e32 v98, v124, v98
	v_mul_f32_e32 v99, v125, v99
	v_cndmask_b32_e32 v118, v120, v118, vcc
	v_mul_f32_e32 v103, v118, v109
	v_mul_f32_e32 v107, v122, v107
	v_mul_f32_e32 v108, v123, v108
	v_cvt_pk_bf16_f32 v102, v106, v107
	v_cvt_pk_bf16_f32 v103, v108, v103
	ds_write_b64 v156, v[102:103] offset:53312
	v_mul_f32_e32 v100, v126, v100
	v_mul_f32_e32 v101, v119, v101
	v_cvt_pk_bf16_f32 v98, v98, v99
	v_cvt_pk_bf16_f32 v99, v100, v101
	ds_write_b64 v156, v[98:99] offset:55616
	ds_read_b128 v[98:101], v157 offset:13056
	ds_read_b128 v[102:105], v157 offset:13120
	s_waitcnt lgkmcnt(1)
	v_mfma_f32_16x16x32_bf16 v[106:109], v[98:101], v[34:37], 0
	v_sub_u32_e32 v120, 0xf0, v155
	ds_read_b128 v[110:113], v157 offset:13184
	ds_read_b128 v[114:117], v157 offset:13248
	v_add_u32_e32 v119, 0xffffff10, v155
	s_waitcnt lgkmcnt(2)
	v_mfma_f32_16x16x32_bf16 v[106:109], v[102:105], v[30:33], v[106:109]
	v_cvt_f32_i32_e32 v120, v120
	v_cvt_f32_i32_e32 v119, v119
	s_movk_i32 s0, 0xf0
	v_mfma_f32_16x16x32_bf16 v[98:101], v[98:101], v[26:29], 0
	v_mul_f32_e32 v120, v142, v120
	v_mul_f32_e32 v119, v144, v119
	v_exp_f32_e32 v120, v120
	s_waitcnt lgkmcnt(1)
	v_mfma_f32_16x16x32_bf16 v[106:109], v[110:113], v[14:17], v[106:109]
	v_exp_f32_e32 v119, v119
	v_cmp_ne_u32_e32 vcc, s0, v155
	v_mul_f32_e32 v125, v120, v154
	v_mfma_f32_16x16x32_bf16 v[98:101], v[102:105], v[22:25], v[98:101]
	v_mul_f32_e32 v124, v119, v153
	v_cndmask_b32_e32 v125, 2.0, v125, vcc
	v_cmp_lt_i32_e32 vcc, s0, v155
	s_waitcnt lgkmcnt(0)
	v_mfma_f32_16x16x32_bf16 v[106:109], v[114:117], v[10:13], v[106:109]
	s_movk_i32 s0, 0xf1
	v_cndmask_b32_e32 v124, v125, v124, vcc
	v_mul_f32_e32 v125, v152, v120
	v_mfma_f32_16x16x32_bf16 v[98:101], v[110:113], v[6:9], v[98:101]
	v_cmp_ne_u32_e32 vcc, s0, v155
	s_nop 2
	v_mul_f32_e32 v106, v124, v106
	v_mul_f32_e32 v124, v151, v119
	v_cndmask_b32_e32 v125, 2.0, v125, vcc
	v_cmp_lt_i32_e32 vcc, s0, v155
	s_movk_i32 s0, 0xf2
	v_mfma_f32_16x16x32_bf16 v[98:101], v[114:117], v[2:5], v[98:101]
	v_cndmask_b32_e32 v124, v125, v124, vcc
	v_mul_f32_e32 v125, v120, v150
	v_cmp_ne_u32_e32 vcc, s0, v155
	v_mul_f32_e32 v107, v124, v107
	v_mul_f32_e32 v124, v119, v149
	v_cndmask_b32_e32 v125, 2.0, v125, vcc
	v_cmp_lt_i32_e32 vcc, s0, v155
	s_movk_i32 s0, 0xf3
	v_mul_f32_e32 v120, v120, v146
	v_cndmask_b32_e32 v124, v125, v124, vcc
	v_cmp_ne_u32_e32 vcc, s0, v155
	v_mul_f32_e32 v119, v119, v148
	v_mul_f32_e32 v98, v121, v98
	v_cndmask_b32_e32 v120, 2.0, v120, vcc
	v_cmp_lt_i32_e32 vcc, s0, v155
	v_mul_f32_e32 v99, v122, v99
	v_mul_f32_e32 v108, v124, v108
	v_cndmask_b32_e32 v102, v120, v119, vcc
	v_mul_f32_e32 v103, v102, v109
	v_cvt_pk_bf16_f32 v102, v106, v107
	v_cvt_pk_bf16_f32 v103, v108, v103
	ds_write_b64 v156, v[102:103] offset:53344
	v_mul_f32_e32 v100, v123, v100
	v_mul_f32_e32 v101, v118, v101
	v_cvt_pk_bf16_f32 v98, v98, v99
	v_cvt_pk_bf16_f32 v99, v100, v101
	ds_write_b64 v156, v[98:99] offset:55648
	s_waitcnt lgkmcnt(0)
	ds_read_b128 v[102:105], v147 offset:53248
	ds_read_b128 v[106:109], v147 offset:53312
	ds_read_b64_tr_b16 v[100:101], v137 offset:18496
	ds_read_b64_tr_b16 v[98:99], v137 offset:17408
	ds_read_b64_tr_b16 v[110:111], v137 offset:17440
	ds_read_b64_tr_b16 v[114:115], v137 offset:17472
	ds_read_b64_tr_b16 v[118:119], v137 offset:17504
	ds_read_b64_tr_b16 v[112:113], v137 offset:18528
	ds_read_b64_tr_b16 v[116:117], v137 offset:18560
	ds_read_b64_tr_b16 v[120:121], v137 offset:18592
	s_waitcnt lgkmcnt(6)
	v_mfma_f32_16x16x32_bf16 v[94:97], v[102:105], v[98:101], v[94:97]
	ds_read_b128 v[122:125], v147 offset:55552
	ds_read_b128 v[126:129], v147 offset:55616
	ds_read_b64_tr_b16 v[132:133], v137 offset:27200
	ds_read_b64_tr_b16 v[130:131], v137 offset:26112
	ds_read_b64_tr_b16 v[146:147], v137 offset:26144
	ds_read_b64_tr_b16 v[150:151], v137 offset:26176
	ds_read_b64_tr_b16 v[154:155], v137 offset:26208
	ds_read_b64_tr_b16 v[148:149], v137 offset:27232
	ds_read_b64_tr_b16 v[152:153], v137 offset:27264
	ds_read_b64_tr_b16 v[156:157], v137 offset:27296
	s_mov_b32 s7, 0
	s_waitcnt lgkmcnt(12)
	v_mfma_f32_16x16x32_bf16 v[90:93], v[102:105], v[110:113], v[90:93]
	s_andn2_b64 vcc, exec, s[30:31]
	s_waitcnt lgkmcnt(9)
	v_mfma_f32_16x16x32_bf16 v[82:85], v[122:125], v[98:101], v[82:85]
	s_waitcnt lgkmcnt(6)
	v_mfma_f32_16x16x32_bf16 v[98:101], v[106:109], v[130:133], v[94:97]
	v_mfma_f32_16x16x32_bf16 v[70:73], v[122:125], v[110:113], v[70:73]
	s_waitcnt lgkmcnt(2)
	v_mfma_f32_16x16x32_bf16 v[94:97], v[106:109], v[146:149], v[90:93]
	v_mfma_f32_16x16x32_bf16 v[86:89], v[102:105], v[114:117], v[86:89]
	v_mfma_f32_16x16x32_bf16 v[66:69], v[122:125], v[114:117], v[66:69]
	v_mfma_f32_16x16x32_bf16 v[78:81], v[102:105], v[118:121], v[78:81]
	v_mfma_f32_16x16x32_bf16 v[62:65], v[122:125], v[118:121], v[62:65]
	ds_read_b64_tr_b16 v[92:93], v137 offset:18624
	ds_read_b64_tr_b16 v[90:91], v137 offset:17536
	ds_read_b64_tr_b16 v[110:111], v137 offset:17568
	ds_read_b64_tr_b16 v[114:115], v137 offset:17600
	ds_read_b64_tr_b16 v[118:119], v137 offset:17632
	ds_read_b64_tr_b16 v[112:113], v137 offset:18656
	ds_read_b64_tr_b16 v[116:117], v137 offset:18688
	ds_read_b64_tr_b16 v[120:121], v137 offset:18720
	s_waitcnt lgkmcnt(6)
	v_mfma_f32_16x16x32_bf16 v[58:61], v[102:105], v[90:93], v[58:61]
	s_waitcnt lgkmcnt(2)
	v_mfma_f32_16x16x32_bf16 v[54:57], v[102:105], v[110:113], v[54:57]
	v_mfma_f32_16x16x32_bf16 v[82:85], v[126:129], v[130:133], v[82:85]
	v_mfma_f32_16x16x32_bf16 v[70:73], v[126:129], v[146:149], v[70:73]
	v_mfma_f32_16x16x32_bf16 v[86:89], v[106:109], v[150:153], v[86:89]
	v_mfma_f32_16x16x32_bf16 v[66:69], v[126:129], v[150:153], v[66:69]
	v_mfma_f32_16x16x32_bf16 v[78:81], v[106:109], v[154:157], v[78:81]
	v_mfma_f32_16x16x32_bf16 v[62:65], v[126:129], v[154:157], v[62:65]
	ds_read_b64_tr_b16 v[132:133], v137 offset:27328
	ds_read_b64_tr_b16 v[130:131], v137 offset:26240
	ds_read_b64_tr_b16 v[146:147], v137 offset:26272
	ds_read_b64_tr_b16 v[150:151], v137 offset:26304
	ds_read_b64_tr_b16 v[154:155], v137 offset:26336
	ds_read_b64_tr_b16 v[148:149], v137 offset:27360
	ds_read_b64_tr_b16 v[152:153], v137 offset:27392
	ds_read_b64_tr_b16 v[156:157], v137 offset:27424
	v_mfma_f32_16x16x32_bf16 v[46:49], v[122:125], v[90:93], v[46:49]
	s_waitcnt lgkmcnt(6)
	v_mfma_f32_16x16x32_bf16 v[90:93], v[106:109], v[130:133], v[58:61]
	v_mfma_f32_16x16x32_bf16 v[42:45], v[122:125], v[110:113], v[42:45]
	s_waitcnt lgkmcnt(2)
	v_mfma_f32_16x16x32_bf16 v[58:61], v[106:109], v[146:149], v[54:57]
	v_mfma_f32_16x16x32_bf16 v[50:53], v[102:105], v[114:117], v[50:53]
	v_mfma_f32_16x16x32_bf16 v[38:41], v[122:125], v[114:117], v[38:41]
	v_mfma_f32_16x16x32_bf16 v[54:57], v[102:105], v[118:121], v[74:77]
	v_mfma_f32_16x16x32_bf16 v[18:21], v[122:125], v[118:121], v[18:21]
	v_mfma_f32_16x16x32_bf16 v[46:49], v[126:129], v[130:133], v[46:49]
	v_mfma_f32_16x16x32_bf16 v[42:45], v[126:129], v[146:149], v[42:45]
	s_waitcnt lgkmcnt(1)
	v_mfma_f32_16x16x32_bf16 v[50:53], v[106:109], v[150:153], v[50:53]
	v_mfma_f32_16x16x32_bf16 v[38:41], v[126:129], v[150:153], v[38:41]
	s_waitcnt lgkmcnt(0)
	v_mfma_f32_16x16x32_bf16 v[54:57], v[106:109], v[154:157], v[54:57]
	v_mfma_f32_16x16x32_bf16 v[18:21], v[126:129], v[154:157], v[18:21]
	s_cbranch_vccnz .LBB0_375
	v_ashrrev_i32_e32 v110, 2, v140
	s_add_u32 s0, s94, s16
	v_lshlrev_b32_e32 v74, 7, v110
	s_addc_u32 s1, s95, s17
	v_ashrrev_i32_e32 v75, 31, v74
	v_lshlrev_b32_e32 v76, 5, v140
	v_lshl_add_u64 v[74:75], v[74:75], 1, s[0:1]
	v_and_b32_e32 v76, 0x60, v76
	v_mov_b32_e32 v77, 0
	v_lshl_add_u64 v[74:75], v[74:75], 0, v[76:77]
	s_barrier
	global_load_dwordx4 v[102:105], v[74:75], off
	global_load_dwordx4 v[106:109], v[74:75], off offset:16
	s_mov_b64 s[98:99], 0x8000
	v_lshl_add_u64 v[216:217], v[74:75], 0, s[98:99]
	global_load_dwordx4 v[220:223], v[74:75], off offset:128
	global_load_dwordx4 v[224:227], v[74:75], off offset:144
	global_load_dwordx4 v[228:231], v[216:217], off
	global_load_dwordx4 v[232:235], v[216:217], off offset:16
	global_load_dwordx4 v[236:239], v[216:217], off offset:128
	global_load_dwordx4 v[208:211], v[216:217], off offset:144
	v_add_u32_e32 v77, 1, v143
	v_add_u32_e32 v111, 17, v143
	v_lshlrev_b32_e32 v134, 16, v26
	v_and_b32_e32 v136, 0xffff0000, v26
	v_cvt_f32_i32_e32 v26, v77
	v_lshlrev_b32_e32 v126, 16, v30
	v_and_b32_e32 v127, 0xffff0000, v30
	v_cvt_f32_i32_e32 v30, v111
	s_movk_i32 s0, 0x90
	v_lshlrev_b32_e32 v138, 16, v28
	v_and_b32_e32 v139, 0xffff0000, v28
	v_mul_lo_u32 v28, v110, s0
	v_mul_f32_e32 v26, v144, v26
	v_exp_f32_e32 v140, v26
	v_add3_u32 v26, 0, v28, v76
	v_mul_f32_e32 v28, v144, v30
	v_exp_f32_e32 v144, v28
	v_lshlrev_b32_e32 v120, 16, v35
	v_and_b32_e32 v121, 0xffff0000, v35
	v_lshlrev_b32_e32 v122, 16, v36
	v_and_b32_e32 v125, 0xffff0000, v37
	v_lshlrev_b32_e32 v130, 16, v32
	v_lshlrev_b32_e32 v137, 16, v27
	v_and_b32_e32 v27, 0xffff0000, v27
	v_lshlrev_b32_e32 v118, 16, v34
	v_and_b32_e32 v119, 0xffff0000, v34
	v_and_b32_e32 v123, 0xffff0000, v36
	v_lshlrev_b32_e32 v124, 16, v37
	v_lshlrev_b32_e32 v128, 16, v31
	v_and_b32_e32 v129, 0xffff0000, v31
	v_and_b32_e32 v131, 0xffff0000, v32
	v_lshlrev_b32_e32 v132, 16, v33
	v_and_b32_e32 v133, 0xffff0000, v33
	v_mul_f32_e32 v31, v140, v120
	v_mul_f32_e32 v32, v140, v121
	v_mul_f32_e32 v33, v140, v122
	v_mul_f32_e32 v36, v140, v125
	v_mul_f32_e32 v111, v140, v130
	v_mul_f32_e32 v146, v144, v27
	v_mul_f32_e32 v28, v140, v118
	v_mul_f32_e32 v30, v140, v119
	v_mul_f32_e32 v34, v140, v123
	v_mul_f32_e32 v35, v140, v124
	v_mul_f32_e32 v112, v140, v131
	v_mul_f32_e32 v117, v144, v137
	v_mul_f32_e32 v147, v144, v138
	v_mul_f32_e32 v148, v144, v139
	v_cvt_pk_bf16_f32 v31, v31, v32
	v_cvt_pk_bf16_f32 v32, v33, v34
	v_cvt_pk_bf16_f32 v33, v35, v36
	v_cvt_pk_bf16_f32 v36, v111, v112
	v_cvt_pk_bf16_f32 v111, v117, v146
	v_lshlrev_b32_e32 v146, 16, v29
	v_and_b32_e32 v149, 0xffff0000, v22
	v_mul_f32_e32 v37, v140, v126
	v_mul_f32_e32 v113, v140, v132
	v_cvt_pk_bf16_f32 v30, v28, v30
	v_cvt_pk_bf16_f32 v112, v147, v148
	v_mul_f32_e32 v28, v144, v146
	v_and_b32_e32 v147, 0xffff0000, v29
	v_lshlrev_b32_e32 v148, 16, v22
	v_mul_f32_e32 v22, v144, v149
	v_mul_f32_e32 v76, v140, v127
	v_mul_f32_e32 v114, v140, v133
	v_cvt_pk_bf16_f32 v34, v37, v76
	v_cvt_pk_bf16_f32 v37, v113, v114
	v_mul_f32_e32 v29, v144, v147
	v_cvt_pk_bf16_f32 v113, v28, v29
	v_mul_f32_e32 v28, v144, v148
	v_mul_f32_e32 v110, v140, v129
	v_mul_f32_e32 v115, v144, v134
	s_waitcnt vmcnt(7)
	ds_write_b128 v26, v[102:105] offset:34816
	s_waitcnt vmcnt(6)
	ds_write_b128 v26, v[106:109] offset:34832
	v_cvt_pk_bf16_f32 v102, v28, v22
	v_add_u32_e32 v22, v145, v135
	s_waitcnt lgkmcnt(0)
	s_barrier
	ds_read_b128 v[104:107], v22 offset:34816
	v_mul_f32_e32 v116, v144, v136
	v_mul_f32_e32 v77, v140, v128
	v_cvt_pk_bf16_f32 v35, v77, v110
	v_cvt_pk_bf16_f32 v110, v115, v116
	ds_read_b128 v[114:117], v22 offset:34880
	s_waitcnt lgkmcnt(1)
	v_mfma_f32_16x16x32_bf16 v[98:101], v[30:33], v[104:107], v[98:101]
	v_and_b32_e32 v151, 0xffff0000, v23
	v_lshlrev_b32_e32 v150, 16, v23
	v_mul_f32_e32 v23, v144, v151
	v_mfma_f32_16x16x32_bf16 v[82:85], v[110:113], v[104:107], v[82:85]
	v_lshlrev_b32_e32 v135, 16, v24
	v_and_b32_e32 v152, 0xffff0000, v24
	v_mul_f32_e32 v28, v144, v150
	v_cvt_pk_bf16_f32 v103, v28, v23
	v_mul_f32_e32 v23, v144, v135
	v_mul_f32_e32 v24, v144, v152
	v_lshlrev_b32_e32 v153, 16, v25
	v_and_b32_e32 v154, 0xffff0000, v25
	v_cvt_pk_bf16_f32 v104, v23, v24
	v_mul_f32_e32 v23, v144, v153
	s_waitcnt lgkmcnt(0)
	v_mfma_f32_16x16x32_bf16 v[98:101], v[34:37], v[114:117], v[98:101]
	v_mul_f32_e32 v24, v144, v154
	v_cvt_pk_bf16_f32 v105, v23, v24
	v_or_b32_e32 v23, 32, v141
	v_mfma_f32_16x16x32_bf16 v[82:85], v[102:105], v[114:117], v[82:85]
	ds_read_b128 v[106:109], v22 offset:37120
	ds_read_b128 v[114:117], v22 offset:37184
	v_mad_u32_u24 v23, v23, s0, v145
	v_lshlrev_b32_e32 v141, 16, v10
	s_waitcnt lgkmcnt(1)
	v_mfma_f32_16x16x32_bf16 v[94:97], v[30:33], v[106:109], v[94:97]
	v_and_b32_e32 v145, 0xffff0000, v10
	v_mul_f32_e32 v10, v140, v145
	v_lshlrev_b32_e32 v155, 16, v11
	v_mfma_f32_16x16x32_bf16 v[70:73], v[110:113], v[106:109], v[70:73]
	v_and_b32_e32 v156, 0xffff0000, v11
	v_mul_f32_e32 v11, v140, v156
	v_lshlrev_b32_e32 v157, 16, v12
	s_waitcnt lgkmcnt(0)
	v_mfma_f32_16x16x32_bf16 v[94:97], v[34:37], v[114:117], v[94:97]
	v_and_b32_e32 v158, 0xffff0000, v12
	v_mul_f32_e32 v12, v140, v158
	v_lshlrev_b32_e32 v159, 16, v13
	v_mfma_f32_16x16x32_bf16 v[70:73], v[102:105], v[114:117], v[70:73]
	ds_read_b128 v[106:109], v23 offset:34816
	ds_read_b128 v[114:117], v23 offset:34880
	v_and_b32_e32 v160, 0xffff0000, v13
	v_mul_f32_e32 v13, v140, v160
	s_waitcnt lgkmcnt(1)
	v_mfma_f32_16x16x32_bf16 v[86:89], v[30:33], v[106:109], v[86:89]
	v_and_b32_e32 v161, 0xffff0000, v6
	v_lshlrev_b32_e32 v162, 16, v7
	v_and_b32_e32 v163, 0xffff0000, v7
	v_mfma_f32_16x16x32_bf16 v[66:69], v[110:113], v[106:109], v[66:69]
	v_mul_f32_e32 v7, v144, v163
	v_lshlrev_b32_e32 v164, 16, v8
	v_and_b32_e32 v165, 0xffff0000, v8
	s_waitcnt lgkmcnt(0)
	v_mfma_f32_16x16x32_bf16 v[86:89], v[34:37], v[114:117], v[86:89]
	v_and_b32_e32 v167, 0xffff0000, v9
	v_mul_f32_e32 v8, v144, v165
	v_lshlrev_b32_e32 v166, 16, v9
	v_mfma_f32_16x16x32_bf16 v[66:69], v[102:105], v[114:117], v[66:69]
	ds_read_b128 v[106:109], v23 offset:37120
	ds_read_b128 v[114:117], v23 offset:37184
	v_mul_f32_e32 v9, v144, v167
	v_lshlrev_b32_e32 v168, 16, v2
	s_waitcnt lgkmcnt(1)
	v_mfma_f32_16x16x32_bf16 v[76:79], v[30:33], v[106:109], v[78:81]
	v_and_b32_e32 v169, 0xffff0000, v2
	v_mul_f32_e32 v2, v144, v169
	v_lshlrev_b32_e32 v170, 16, v3
	v_mfma_f32_16x16x32_bf16 v[62:65], v[110:113], v[106:109], v[62:65]
	v_and_b32_e32 v171, 0xffff0000, v3
	v_mul_f32_e32 v3, v144, v171
	v_lshlrev_b32_e32 v172, 16, v4
	s_waitcnt lgkmcnt(0)
	v_mfma_f32_16x16x32_bf16 v[76:79], v[34:37], v[114:117], v[76:79]
	v_and_b32_e32 v173, 0xffff0000, v4
	v_and_b32_e32 v175, 0xffff0000, v5
	v_mul_f32_e32 v4, v144, v173
	v_mfma_f32_16x16x32_bf16 v[62:65], v[102:105], v[114:117], v[62:65]
	ds_read_b128 v[106:109], v22 offset:44032
	ds_read_b128 v[114:117], v22 offset:44096
	v_lshlrev_b32_e32 v174, 16, v5
	v_mul_f32_e32 v5, v144, v175
	s_waitcnt lgkmcnt(1)
	v_mfma_f32_16x16x32_bf16 v[90:93], v[30:33], v[106:109], v[90:93]
	s_mov_b64 s[0:1], 0x8000
	v_mfma_f32_16x16x32_bf16 v[46:49], v[110:113], v[106:109], v[46:49]
	s_waitcnt lgkmcnt(0)
	v_mfma_f32_16x16x32_bf16 v[90:93], v[34:37], v[114:117], v[90:93]
	v_mfma_f32_16x16x32_bf16 v[46:49], v[102:105], v[114:117], v[46:49]
	ds_read_b128 v[106:109], v22 offset:46336
	ds_read_b128 v[114:117], v22 offset:46400
	s_waitcnt lgkmcnt(1)
	v_mfma_f32_16x16x32_bf16 v[58:61], v[30:33], v[106:109], v[58:61]
	v_mfma_f32_16x16x32_bf16 v[42:45], v[110:113], v[106:109], v[42:45]
	s_waitcnt lgkmcnt(0)
	v_mfma_f32_16x16x32_bf16 v[58:61], v[34:37], v[114:117], v[58:61]
	v_mfma_f32_16x16x32_bf16 v[42:45], v[102:105], v[114:117], v[42:45]
	ds_read_b128 v[106:109], v22 offset:48640
	ds_read_b128 v[114:117], v22 offset:48704
	s_waitcnt lgkmcnt(1)
	v_mfma_f32_16x16x32_bf16 v[50:53], v[30:33], v[106:109], v[50:53]
	v_mfma_f32_16x16x32_bf16 v[38:41], v[110:113], v[106:109], v[38:41]
	s_waitcnt lgkmcnt(0)
	v_mfma_f32_16x16x32_bf16 v[50:53], v[34:37], v[114:117], v[50:53]
	v_mfma_f32_16x16x32_bf16 v[38:41], v[102:105], v[114:117], v[38:41]
	ds_read_b128 v[106:109], v22 offset:50944
	ds_read_b128 v[114:117], v22 offset:51008
	s_waitcnt lgkmcnt(0)
	s_barrier
	v_mfma_f32_16x16x32_bf16 v[28:31], v[30:33], v[106:109], v[54:57]
	v_mfma_f32_16x16x32_bf16 v[28:31], v[34:37], v[114:117], v[28:31]
	s_nop 0
	s_waitcnt vmcnt(5)
	ds_write_b128 v26, v[220:223] offset:34816
	s_waitcnt vmcnt(4)
	ds_write_b128 v26, v[224:227] offset:34832
	v_mfma_f32_16x16x32_bf16 v[18:21], v[110:113], v[106:109], v[18:21]
	v_lshlrev_b32_e32 v110, 16, v14
	v_and_b32_e32 v111, 0xffff0000, v14
	v_mul_f32_e32 v24, v140, v110
	v_mul_f32_e32 v14, v140, v111
	v_lshlrev_b32_e32 v112, 16, v15
	v_and_b32_e32 v113, 0xffff0000, v15
	v_mfma_f32_16x16x32_bf16 v[18:21], v[102:105], v[114:117], v[18:21]
	v_cvt_pk_bf16_f32 v14, v24, v14
	v_mul_f32_e32 v24, v140, v112
	v_mul_f32_e32 v15, v140, v113
	v_lshlrev_b32_e32 v114, 16, v16
	v_and_b32_e32 v115, 0xffff0000, v16
	v_cvt_pk_bf16_f32 v15, v24, v15
	v_mul_f32_e32 v24, v140, v114
	v_mul_f32_e32 v16, v140, v115
	v_lshlrev_b32_e32 v116, 16, v17
	v_and_b32_e32 v117, 0xffff0000, v17
	v_cvt_pk_bf16_f32 v16, v24, v16
	v_mul_f32_e32 v24, v140, v116
	v_mul_f32_e32 v17, v140, v117
	v_cvt_pk_bf16_f32 v17, v24, v17
	v_mul_f32_e32 v24, v140, v141
	v_cvt_pk_bf16_f32 v10, v24, v10
	v_mul_f32_e32 v24, v140, v155
	s_waitcnt lgkmcnt(0)
	s_barrier
	v_cvt_pk_bf16_f32 v11, v24, v11
	v_mul_f32_e32 v24, v140, v157
	ds_read_b128 v[32:35], v22 offset:34816
	ds_read_b128 v[54:57], v22 offset:34880
	v_cvt_pk_bf16_f32 v12, v24, v12
	v_mul_f32_e32 v24, v140, v159
	v_lshlrev_b32_e32 v140, 16, v6
	v_cvt_pk_bf16_f32 v13, v24, v13
	v_mul_f32_e32 v24, v144, v140
	v_mul_f32_e32 v6, v144, v161
	v_cvt_pk_bf16_f32 v6, v24, v6
	v_mul_f32_e32 v24, v144, v162
	v_cvt_pk_bf16_f32 v7, v24, v7
	v_mul_f32_e32 v24, v144, v164
	v_cvt_pk_bf16_f32 v8, v24, v8
	v_mul_f32_e32 v24, v144, v166
	v_cvt_pk_bf16_f32 v9, v24, v9
	s_waitcnt lgkmcnt(1)
	v_mfma_f32_16x16x32_bf16 v[98:101], v[14:17], v[32:35], v[98:101]
	v_mul_f32_e32 v24, v144, v168
	v_cvt_pk_bf16_f32 v2, v24, v2
	v_mul_f32_e32 v24, v144, v170
	v_mfma_f32_16x16x32_bf16 v[32:35], v[6:9], v[32:35], v[82:85]
	v_cvt_pk_bf16_f32 v3, v24, v3
	v_mul_f32_e32 v24, v144, v172
	v_cvt_pk_bf16_f32 v4, v24, v4
	v_mul_f32_e32 v24, v144, v174
	s_waitcnt lgkmcnt(0)
	v_mfma_f32_16x16x32_bf16 v[80:83], v[10:13], v[54:57], v[98:101]
	v_cvt_pk_bf16_f32 v5, v24, v5
	v_lshl_add_u64 v[24:25], v[74:75], 0, s[0:1]
	s_mov_b32 s0, 0x8000
	v_mfma_f32_16x16x32_bf16 v[32:35], v[2:5], v[54:57], v[32:35]
	ds_read_b128 v[54:57], v22 offset:37120
	ds_read_b128 v[98:101], v22 offset:37184
	s_waitcnt lgkmcnt(1)
	v_mfma_f32_16x16x32_bf16 v[94:97], v[14:17], v[54:57], v[94:97]
	v_mfma_f32_16x16x32_bf16 v[54:57], v[6:9], v[54:57], v[70:73]
	s_waitcnt lgkmcnt(0)
	v_mfma_f32_16x16x32_bf16 v[70:73], v[10:13], v[98:101], v[94:97]
	v_mfma_f32_16x16x32_bf16 v[54:57], v[2:5], v[98:101], v[54:57]
	s_nop 3
	ds_read_b128 v[94:97], v23 offset:34816
	ds_read_b128 v[98:101], v23 offset:34880
	s_waitcnt lgkmcnt(1)
	v_mfma_f32_16x16x32_bf16 v[84:87], v[14:17], v[94:97], v[86:89]
	v_mfma_f32_16x16x32_bf16 v[66:69], v[6:9], v[94:97], v[66:69]
	s_waitcnt lgkmcnt(0)
	v_mfma_f32_16x16x32_bf16 v[84:87], v[10:13], v[98:101], v[84:87]
	v_mfma_f32_16x16x32_bf16 v[66:69], v[2:5], v[98:101], v[66:69]
	ds_read_b128 v[94:97], v23 offset:37120
	ds_read_b128 v[98:101], v23 offset:37184
	s_waitcnt lgkmcnt(1)
	v_mfma_f32_16x16x32_bf16 v[76:79], v[14:17], v[94:97], v[76:79]
	v_mfma_f32_16x16x32_bf16 v[62:65], v[6:9], v[94:97], v[62:65]
	s_waitcnt lgkmcnt(0)
	v_mfma_f32_16x16x32_bf16 v[76:79], v[10:13], v[98:101], v[76:79]
	v_mfma_f32_16x16x32_bf16 v[62:65], v[2:5], v[98:101], v[62:65]
	ds_read_b128 v[94:97], v22 offset:44032
	ds_read_b128 v[98:101], v22 offset:44096
	s_waitcnt lgkmcnt(1)
	v_mfma_f32_16x16x32_bf16 v[88:91], v[14:17], v[94:97], v[90:93]
	v_mfma_f32_16x16x32_bf16 v[46:49], v[6:9], v[94:97], v[46:49]
	s_waitcnt lgkmcnt(0)
	v_mfma_f32_16x16x32_bf16 v[88:91], v[10:13], v[98:101], v[88:91]
	v_mfma_f32_16x16x32_bf16 v[46:49], v[2:5], v[98:101], v[46:49]
	ds_read_b128 v[92:95], v22 offset:46336
	ds_read_b128 v[96:99], v22 offset:46400
	v_add_co_u32_e32 v100, vcc, s0, v74
	s_waitcnt lgkmcnt(1)
	v_mfma_f32_16x16x32_bf16 v[58:61], v[14:17], v[92:95], v[58:61]
	v_addc_co_u32_e32 v101, vcc, 0, v75, vcc
	s_mov_b64 s[0:1], 0x8080
	v_mfma_f32_16x16x32_bf16 v[42:45], v[6:9], v[92:95], v[42:45]
	s_waitcnt lgkmcnt(0)
	v_mfma_f32_16x16x32_bf16 v[58:61], v[10:13], v[96:99], v[58:61]
	v_mfma_f32_16x16x32_bf16 v[42:45], v[2:5], v[96:99], v[42:45]
	ds_read_b128 v[92:95], v22 offset:48640
	ds_read_b128 v[96:99], v22 offset:48704
	s_waitcnt lgkmcnt(1)
	v_mfma_f32_16x16x32_bf16 v[50:53], v[14:17], v[92:95], v[50:53]
	v_mfma_f32_16x16x32_bf16 v[36:39], v[6:9], v[92:95], v[38:41]
	s_waitcnt lgkmcnt(0)
	v_mfma_f32_16x16x32_bf16 v[50:53], v[10:13], v[96:99], v[50:53]
	v_mfma_f32_16x16x32_bf16 v[36:39], v[2:5], v[96:99], v[36:39]
	ds_read_b128 v[92:95], v22 offset:50944
	ds_read_b128 v[96:99], v22 offset:51008
	s_waitcnt lgkmcnt(0)
	s_barrier
	v_mfma_f32_16x16x32_bf16 v[14:17], v[14:17], v[92:95], v[28:31]
	v_mfma_f32_16x16x32_bf16 v[6:9], v[6:9], v[92:95], v[18:21]
	s_nop 2
	s_waitcnt vmcnt(3)
	ds_write_b128 v26, v[228:231] offset:34816
	s_waitcnt vmcnt(2)
	ds_write_b128 v26, v[232:235] offset:34832
	v_mfma_f32_16x16x32_bf16 v[10:13], v[10:13], v[96:99], v[14:17]
	s_waitcnt lgkmcnt(0)
	s_barrier
	s_nop 0
	v_sub_u32_e32 v14, 0x100, v143
	v_cvt_f32_i32_e32 v14, v14
	v_sub_u32_e32 v15, 0xf0, v143
	v_cvt_f32_i32_e32 v15, v15
	v_mfma_f32_16x16x32_bf16 v[2:5], v[2:5], v[96:99], v[6:9]
	ds_read_b128 v[28:31], v22 offset:34816
	ds_read_b128 v[96:99], v22 offset:34880
	s_nop 0
	v_mul_f32_e32 v6, v142, v14
	v_exp_f32_e32 v24, v6
	v_mul_f32_e32 v6, v142, v15
	v_exp_f32_e32 v142, v6
	v_mul_f32_e32 v6, v24, v118
	v_mul_f32_e32 v7, v24, v119
	v_cvt_pk_bf16_f32 v6, v6, v7
	v_mul_f32_e32 v7, v24, v120
	v_mul_f32_e32 v8, v24, v121
	v_cvt_pk_bf16_f32 v7, v7, v8
	v_mul_f32_e32 v8, v24, v122
	v_mul_f32_e32 v9, v24, v123
	v_cvt_pk_bf16_f32 v8, v8, v9
	v_mul_f32_e32 v9, v24, v124
	v_mul_f32_e32 v14, v24, v125
	v_cvt_pk_bf16_f32 v9, v9, v14
	v_mul_f32_e32 v14, v24, v126
	v_mul_f32_e32 v15, v24, v127
	v_cvt_pk_bf16_f32 v14, v14, v15
	v_mul_f32_e32 v15, v24, v128
	v_mul_f32_e32 v16, v24, v129
	v_cvt_pk_bf16_f32 v15, v15, v16
	v_mul_f32_e32 v16, v24, v130
	v_mul_f32_e32 v17, v24, v131
	v_cvt_pk_bf16_f32 v16, v16, v17
	v_mul_f32_e32 v17, v24, v132
	v_mul_f32_e32 v18, v24, v133
	v_cvt_pk_bf16_f32 v17, v17, v18
	v_mul_f32_e32 v18, v142, v134
	v_mul_f32_e32 v19, v142, v136
	v_cvt_pk_bf16_f32 v18, v18, v19
	v_mul_f32_e32 v19, v142, v137
	v_mul_f32_e32 v20, v142, v27
	v_cvt_pk_bf16_f32 v19, v19, v20
	v_mul_f32_e32 v20, v142, v138
	v_mul_f32_e32 v21, v142, v139
	v_cvt_pk_bf16_f32 v20, v20, v21
	v_mul_f32_e32 v21, v142, v146
	v_mul_f32_e32 v25, v142, v147
	v_cvt_pk_bf16_f32 v21, v21, v25
	s_waitcnt lgkmcnt(1)
	v_mfma_f32_16x16x32_bf16 v[80:83], v[6:9], v[28:31], v[80:83]
	v_mul_f32_e32 v25, v142, v148
	v_mul_f32_e32 v27, v142, v149
	v_cvt_pk_bf16_f32 v92, v25, v27
	v_mfma_f32_16x16x32_bf16 v[28:31], v[18:21], v[28:31], v[32:35]
	v_mul_f32_e32 v25, v142, v150
	v_mul_f32_e32 v27, v142, v151
	v_cvt_pk_bf16_f32 v93, v25, v27
	v_mul_f32_e32 v25, v142, v135
	v_mul_f32_e32 v27, v142, v152
	v_cvt_pk_bf16_f32 v94, v25, v27
	s_waitcnt lgkmcnt(0)
	v_mfma_f32_16x16x32_bf16 v[32:35], v[14:17], v[96:99], v[80:83]
	v_mul_f32_e32 v25, v142, v153
	v_mul_f32_e32 v27, v142, v154
	v_cvt_pk_bf16_f32 v95, v25, v27
	s_nop 0
	v_mfma_f32_16x16x32_bf16 v[28:31], v[92:95], v[96:99], v[28:31]
	ds_read_b128 v[80:83], v22 offset:37120
	ds_read_b128 v[96:99], v22 offset:37184
	s_waitcnt lgkmcnt(1)
	v_mfma_f32_16x16x32_bf16 v[70:73], v[6:9], v[80:83], v[70:73]
	v_mfma_f32_16x16x32_bf16 v[54:57], v[18:21], v[80:83], v[54:57]
	s_waitcnt lgkmcnt(0)
	v_mfma_f32_16x16x32_bf16 v[70:73], v[14:17], v[96:99], v[70:73]
	v_mfma_f32_16x16x32_bf16 v[54:57], v[92:95], v[96:99], v[54:57]
	ds_read_b128 v[80:83], v23 offset:34816
	ds_read_b128 v[96:99], v23 offset:34880
	s_waitcnt lgkmcnt(1)
	v_mfma_f32_16x16x32_bf16 v[84:87], v[6:9], v[80:83], v[84:87]
	v_mfma_f32_16x16x32_bf16 v[66:69], v[18:21], v[80:83], v[66:69]
	s_waitcnt lgkmcnt(0)
	v_mfma_f32_16x16x32_bf16 v[102:105], v[14:17], v[96:99], v[84:87]
	ds_read_b128 v[80:83], v23 offset:37120
	s_nop 3
	ds_read_b128 v[84:87], v23 offset:37184
	s_waitcnt lgkmcnt(1)
	v_mfma_f32_16x16x32_bf16 v[76:79], v[6:9], v[80:83], v[76:79]
	v_mfma_f32_16x16x32_bf16 v[62:65], v[18:21], v[80:83], v[62:65]
	s_waitcnt lgkmcnt(0)
	v_mfma_f32_16x16x32_bf16 v[76:79], v[14:17], v[84:87], v[76:79]
	v_mfma_f32_16x16x32_bf16 v[62:65], v[92:95], v[84:87], v[62:65]
	ds_read_b128 v[80:83], v22 offset:44032
	ds_read_b128 v[84:87], v22 offset:44096
	s_waitcnt lgkmcnt(1)
	v_mfma_f32_16x16x32_bf16 v[88:91], v[6:9], v[80:83], v[88:91]
	v_mfma_f32_16x16x32_bf16 v[46:49], v[18:21], v[80:83], v[46:49]
	s_waitcnt lgkmcnt(0)
	v_mfma_f32_16x16x32_bf16 v[106:109], v[14:17], v[84:87], v[88:91]
	v_mfma_f32_16x16x32_bf16 v[46:49], v[92:95], v[84:87], v[46:49]
	ds_read_b128 v[80:83], v22 offset:46336
	ds_read_b128 v[84:87], v22 offset:46400
	s_waitcnt lgkmcnt(1)
	v_mfma_f32_16x16x32_bf16 v[58:61], v[6:9], v[80:83], v[58:61]
	v_mfma_f32_16x16x32_bf16 v[40:43], v[18:21], v[80:83], v[42:45]
	s_waitcnt lgkmcnt(0)
	v_mfma_f32_16x16x32_bf16 v[58:61], v[14:17], v[84:87], v[58:61]
	s_nop 0
	v_mul_f32_e32 v44, v142, v168
	v_mul_f32_e32 v45, v142, v169
	v_mfma_f32_16x16x32_bf16 v[40:43], v[92:95], v[84:87], v[40:43]
	ds_read_b128 v[80:83], v22 offset:48640
	ds_read_b128 v[84:87], v22 offset:48704
	s_waitcnt lgkmcnt(1)
	v_mfma_f32_16x16x32_bf16 v[50:53], v[6:9], v[80:83], v[50:53]
	v_mfma_f32_16x16x32_bf16 v[36:39], v[18:21], v[80:83], v[36:39]
	s_waitcnt lgkmcnt(0)
	v_mfma_f32_16x16x32_bf16 v[50:53], v[14:17], v[84:87], v[50:53]
	v_mfma_f32_16x16x32_bf16 v[36:39], v[92:95], v[84:87], v[36:39]
	ds_read_b128 v[80:83], v22 offset:50944
	ds_read_b128 v[84:87], v22 offset:51008
	s_waitcnt lgkmcnt(0)
	s_barrier
	v_mfma_f32_16x16x32_bf16 v[6:9], v[6:9], v[80:83], v[10:13]
	v_mfma_f32_16x16x32_bf16 v[6:9], v[14:17], v[84:87], v[6:9]
	v_lshl_add_u64 v[14:15], v[74:75], 0, s[0:1]
	s_nop 0
	s_nop 0
	s_waitcnt vmcnt(1)
	ds_write_b128 v26, v[236:239] offset:34816
	s_waitcnt vmcnt(0)
	ds_write_b128 v26, v[208:211] offset:34832
	v_mul_f32_e32 v10, v24, v110
	v_mul_f32_e32 v11, v24, v111
	v_cvt_pk_bf16_f32 v10, v10, v11
	v_mul_f32_e32 v11, v24, v112
	v_mul_f32_e32 v12, v24, v113
	v_cvt_pk_bf16_f32 v11, v11, v12
	v_mul_f32_e32 v12, v24, v114
	v_mul_f32_e32 v13, v24, v115
	v_cvt_pk_bf16_f32 v12, v12, v13
	v_mul_f32_e32 v13, v24, v116
	v_mul_f32_e32 v14, v24, v117
	v_cvt_pk_bf16_f32 v13, v13, v14
	v_mul_f32_e32 v14, v24, v141
	v_mul_f32_e32 v15, v24, v145
	v_cvt_pk_bf16_f32 v14, v14, v15
	v_mul_f32_e32 v15, v24, v155
	v_mul_f32_e32 v16, v24, v156
	v_cvt_pk_bf16_f32 v15, v15, v16
	v_mul_f32_e32 v16, v24, v157
	v_mul_f32_e32 v17, v24, v158
	v_mfma_f32_16x16x32_bf16 v[2:5], v[18:21], v[80:83], v[2:5]
	v_cvt_pk_bf16_f32 v16, v16, v17
	v_mul_f32_e32 v17, v24, v159
	v_mul_f32_e32 v18, v24, v160
	v_cvt_pk_bf16_f32 v17, v17, v18
	v_mul_f32_e32 v18, v142, v140
	v_mul_f32_e32 v19, v142, v161
	v_cvt_pk_bf16_f32 v18, v18, v19
	v_mul_f32_e32 v19, v142, v162
	v_mul_f32_e32 v20, v142, v163
	v_cvt_pk_bf16_f32 v19, v19, v20
	v_mul_f32_e32 v20, v142, v164
	v_mul_f32_e32 v21, v142, v165
	v_cvt_pk_bf16_f32 v20, v20, v21
	v_mul_f32_e32 v21, v142, v166
	v_mul_f32_e32 v24, v142, v167
	s_waitcnt lgkmcnt(0)
	s_barrier
	v_cvt_pk_bf16_f32 v21, v21, v24
	ds_read_b128 v[24:27], v22 offset:34816
	ds_read_b128 v[80:83], v22 offset:34880
	s_waitcnt lgkmcnt(1)
	v_mfma_f32_16x16x32_bf16 v[32:35], v[10:13], v[24:27], v[32:35]
	v_cvt_pk_bf16_f32 v110, v44, v45
	v_mul_f32_e32 v44, v142, v170
	v_mul_f32_e32 v45, v142, v171
	v_mfma_f32_16x16x32_bf16 v[24:27], v[18:21], v[24:27], v[28:31]
	v_cvt_pk_bf16_f32 v111, v44, v45
	v_mfma_f32_16x16x32_bf16 v[66:69], v[92:95], v[96:99], v[66:69]
	s_nop 1
	v_mul_f32_e32 v28, v142, v172
	v_mul_f32_e32 v29, v142, v173
	v_cvt_pk_bf16_f32 v112, v28, v29
	v_mul_f32_e32 v28, v142, v174
	v_mul_f32_e32 v29, v142, v175
	v_mfma_f32_16x16x32_bf16 v[2:5], v[92:95], v[84:87], v[2:5]
	v_cvt_pk_bf16_f32 v113, v28, v29
	s_waitcnt lgkmcnt(0)
	v_mfma_f32_16x16x32_bf16 v[98:101], v[14:17], v[80:83], v[32:35]
	v_mfma_f32_16x16x32_bf16 v[82:85], v[110:113], v[80:83], v[24:27]
	s_nop 2
	ds_read_b128 v[24:27], v22 offset:37120
	ds_read_b128 v[28:31], v22 offset:37184
	s_waitcnt lgkmcnt(1)
	v_mfma_f32_16x16x32_bf16 v[32:35], v[10:13], v[24:27], v[70:73]
	v_mfma_f32_16x16x32_bf16 v[24:27], v[18:21], v[24:27], v[54:57]
	s_waitcnt lgkmcnt(0)
	v_mfma_f32_16x16x32_bf16 v[94:97], v[14:17], v[28:31], v[32:35]
	v_mfma_f32_16x16x32_bf16 v[70:73], v[110:113], v[28:31], v[24:27]
	s_nop 4
	ds_read_b128 v[24:27], v23 offset:34816
	ds_read_b128 v[28:31], v23 offset:34880
	s_waitcnt lgkmcnt(1)
	v_mfma_f32_16x16x32_bf16 v[32:35], v[10:13], v[24:27], v[102:105]
	v_mfma_f32_16x16x32_bf16 v[24:27], v[18:21], v[24:27], v[66:69]
	s_waitcnt lgkmcnt(0)
	v_mfma_f32_16x16x32_bf16 v[86:89], v[14:17], v[28:31], v[32:35]
	v_mfma_f32_16x16x32_bf16 v[66:69], v[110:113], v[28:31], v[24:27]
	s_nop 4
	ds_read_b128 v[24:27], v23 offset:37120
	ds_read_b128 v[28:31], v23 offset:37184
	s_waitcnt lgkmcnt(1)
	v_mfma_f32_16x16x32_bf16 v[32:35], v[10:13], v[24:27], v[76:79]
	v_mfma_f32_16x16x32_bf16 v[24:27], v[18:21], v[24:27], v[62:65]
	s_waitcnt lgkmcnt(0)
	v_mfma_f32_16x16x32_bf16 v[78:81], v[14:17], v[28:31], v[32:35]
	v_mfma_f32_16x16x32_bf16 v[62:65], v[110:113], v[28:31], v[24:27]
	s_nop 4
	ds_read_b128 v[24:27], v22 offset:44032
	ds_read_b128 v[28:31], v22 offset:44096
	s_waitcnt lgkmcnt(1)
	v_mfma_f32_16x16x32_bf16 v[32:35], v[10:13], v[24:27], v[106:109]
	v_mfma_f32_16x16x32_bf16 v[24:27], v[18:21], v[24:27], v[46:49]
	s_waitcnt lgkmcnt(0)
	v_mfma_f32_16x16x32_bf16 v[90:93], v[14:17], v[28:31], v[32:35]
	v_mfma_f32_16x16x32_bf16 v[46:49], v[110:113], v[28:31], v[24:27]
	s_nop 4
	ds_read_b128 v[24:27], v22 offset:46336
	ds_read_b128 v[28:31], v22 offset:46400
	s_waitcnt lgkmcnt(1)
	v_mfma_f32_16x16x32_bf16 v[32:35], v[10:13], v[24:27], v[58:61]
	v_mfma_f32_16x16x32_bf16 v[24:27], v[18:21], v[24:27], v[40:43]
	s_waitcnt lgkmcnt(0)
	v_mfma_f32_16x16x32_bf16 v[58:61], v[14:17], v[28:31], v[32:35]
	v_mfma_f32_16x16x32_bf16 v[42:45], v[110:113], v[28:31], v[24:27]
	s_nop 4
	ds_read_b128 v[24:27], v22 offset:48640
	ds_read_b128 v[28:31], v22 offset:48704
	s_waitcnt lgkmcnt(1)
	v_mfma_f32_16x16x32_bf16 v[32:35], v[10:13], v[24:27], v[50:53]
	v_mfma_f32_16x16x32_bf16 v[24:27], v[18:21], v[24:27], v[36:39]
	s_waitcnt lgkmcnt(0)
	v_mfma_f32_16x16x32_bf16 v[50:53], v[14:17], v[28:31], v[32:35]
	v_mfma_f32_16x16x32_bf16 v[38:41], v[110:113], v[28:31], v[24:27]
	s_nop 4
	ds_read_b128 v[24:27], v22 offset:50944
	ds_read_b128 v[28:31], v22 offset:51008
	s_waitcnt lgkmcnt(1)
	v_mfma_f32_16x16x32_bf16 v[6:9], v[10:13], v[24:27], v[6:9]
	v_mfma_f32_16x16x32_bf16 v[2:5], v[18:21], v[24:27], v[2:5]
	s_waitcnt lgkmcnt(0)
	v_mfma_f32_16x16x32_bf16 v[54:57], v[14:17], v[28:31], v[6:9]
	v_mfma_f32_16x16x32_bf16 v[18:21], v[110:113], v[28:31], v[2:5]
